# EpiNorm step 1 (P6 and both P10 variants): second-half residual/gate loads issued together with the first-half loads into spare VGPRs, waits recomputed
# baseline (speedup 1.0000x reference)
.LBB0_708:
	v_readlane_b32 s16, v254, 0
	v_readlane_b32 s36, v254, 10
	s_cmp_eq_u32 s0, 0
	v_readlane_b32 s22, v254, 6
	v_readlane_b32 s23, v254, 7
	v_readlane_b32 s37, v254, 11
	s_cselect_b32 s15, s37, s23
	s_cselect_b32 s14, s36, s22
	s_lshl_b32 s3, s8, 8
	s_add_i32 s9, s3, s30
	s_lshl_b32 s4, s26, 5
	v_or_b32_e32 v128, s9, v143
	s_lshl_b32 s9, s12, 8
	v_lshrrev_b32_e32 v129, 1, v142
	s_or_b32 s4, s9, s4
	v_and_b32_e32 v130, 64, v227
	v_and_or_b32 v144, v129, 24, s4
	v_xor_b32_e32 v129, 16, v227
	v_add_u32_e32 v130, 64, v130
	v_cmp_lt_i32_e32 vcc, v129, v130
	v_ashrrev_i32_e32 v145, 31, v144
	s_barrier
	v_cndmask_b32_e32 v129, v227, v129, vcc
	v_lshlrev_b32_e32 v133, 2, v129
	v_xor_b32_e32 v129, 32, v227
	v_cmp_lt_i32_e32 vcc, v129, v130
	s_lshl_b32 s4, s26, 2
	v_and_b32_e32 v132, 63, v142
	v_cndmask_b32_e32 v129, v227, v129, vcc
	v_lshlrev_b32_e32 v134, 2, v129
	v_ashrrev_i32_e32 v129, 31, v128
	v_lshlrev_b64 v[130:131], 10, v[128:129]
	v_lshl_add_u64 v[130:131], v[130:131], 0, v[144:145]
	v_lshlrev_b64 v[130:131], 2, v[130:131]
	v_lshl_add_u64 v[140:141], s[14:15], 0, v[130:131]
	global_load_dwordx4 v[136:139], v[140:141], off offset:16 nt
	global_load_dwordx4 v[148:151], v[140:141], off nt
	global_load_dwordx4 v[168:171], v[140:141], off offset:528 nt
	global_load_dwordx4 v[172:175], v[140:141], off offset:512 nt
	v_lshl_add_u64 v[130:131], s[22:23], 0, v[130:131]
	s_add_i32 s4, s4, 0
	v_readlane_b32 s17, v254, 1
	v_cmp_gt_u32_e32 vcc, 16, v132
	v_readlane_b32 s18, v254, 2
	v_readlane_b32 s19, v254, 3
	v_readlane_b32 s20, v254, 4
	v_readlane_b32 s21, v254, 5
	v_readlane_b32 s38, v254, 12
	v_readlane_b32 s39, v254, 13
	v_readlane_b32 s40, v254, 14
	v_readlane_b32 s41, v254, 15
	v_readlane_b32 s42, v254, 16
	v_readlane_b32 s43, v254, 17
	v_readlane_b32 s44, v254, 18
	v_readlane_b32 s45, v254, 19
	v_readlane_b32 s46, v254, 20
	v_readlane_b32 s47, v254, 21
	v_readlane_b32 s48, v254, 22
	v_readlane_b32 s49, v254, 23
	v_readlane_b32 s50, v254, 24
	v_readlane_b32 s51, v254, 25
	s_waitcnt vmcnt(2)
	v_pk_add_f32 v[64:65], v[64:65], v[136:137]
	v_pk_add_f32 v[70:71], v[70:71], v[150:151]
	v_pk_add_f32 v[68:69], v[68:69], v[148:149]
	v_mul_f32_e32 v136, v71, v71
	v_mul_f32_e32 v135, v69, v69
	v_fmac_f32_e32 v135, v68, v68
	v_fmac_f32_e32 v136, v70, v70
	v_add_f32_e32 v135, v135, v136
	v_mul_f32_e32 v136, v65, v65
	v_pk_add_f32 v[66:67], v[66:67], v[138:139]
	v_fmac_f32_e32 v136, v64, v64
	v_add_f32_e32 v135, v135, v136
	v_mul_f32_e32 v136, v67, v67
	global_store_dwordx4 v[130:131], v[68:71], off nt
	global_store_dwordx4 v[130:131], v[64:67], off offset:16 nt
	v_fmac_f32_e32 v136, v66, v66
	v_add_f32_e32 v135, v136, v135
	s_waitcnt vmcnt(3)
	v_pk_add_f32 v[102:103], v[102:103], v[170:171]
	s_waitcnt vmcnt(2)
	v_pk_add_f32 v[98:99], v[98:99], v[174:175]
	v_pk_add_f32 v[96:97], v[96:97], v[172:173]
	v_pk_add_f32 v[100:101], v[100:101], v[168:169]
	global_store_dwordx4 v[130:131], v[96:99], off offset:512 nt
	global_store_dwordx4 v[130:131], v[100:103], off offset:528 nt
	v_mul_f32_e32 v130, v97, v97
	v_mul_f32_e32 v131, v99, v99
	v_fmac_f32_e32 v130, v96, v96
	v_fmac_f32_e32 v131, v98, v98
	v_add_f32_e32 v130, v130, v131
	v_mul_f32_e32 v131, v101, v101
	v_fmac_f32_e32 v131, v100, v100
	v_add_f32_e32 v130, v130, v131
	v_mul_f32_e32 v131, v103, v103
	v_fmac_f32_e32 v131, v102, v102
	v_add_f32_e32 v130, v131, v130
	v_add_f32_e32 v130, v135, v130
	ds_bpermute_b32 v131, v133, v130
	v_lshl_add_u32 v135, v146, 4, s4
	s_waitcnt lgkmcnt(0)
	v_add_f32_e32 v130, v130, v131
	ds_bpermute_b32 v131, v134, v130
	s_and_saveexec_b64 s[16:17], vcc
	s_mov_b64 s[34:35], 0x800
	s_cbranch_execz .LBB0_710
	s_waitcnt lgkmcnt(0)
	v_add_f32_e32 v130, v130, v131
	ds_write_b32 v135, v130
.LBB0_710:
	s_or_b64 exec, exec, s[16:17]
	v_or_b32_e32 v130, 16, v128
	s_waitcnt lgkmcnt(0)
	v_ashrrev_i32_e32 v131, 31, v130
	v_lshlrev_b64 v[130:131], 10, v[130:131]
	v_lshl_add_u64 v[130:131], v[130:131], 0, v[144:145]
	v_lshlrev_b64 v[130:131], 2, v[130:131]
	v_lshl_add_u64 v[140:141], s[14:15], 0, v[130:131]
	global_load_dwordx4 v[136:139], v[140:141], off offset:16 nt
	global_load_dwordx4 v[148:151], v[140:141], off nt
	global_load_dwordx4 v[168:171], v[140:141], off offset:528 nt
	global_load_dwordx4 v[172:175], v[140:141], off offset:512 nt
	v_readlane_b32 s16, v254, 0
	v_readlane_b32 s22, v254, 6
	v_readlane_b32 s23, v254, 7
	v_readlane_b32 s17, v254, 1
	v_readlane_b32 s18, v254, 2
	v_lshl_add_u64 v[130:131], s[22:23], 0, v[130:131]
	v_readlane_b32 s19, v254, 3
	v_readlane_b32 s20, v254, 4
	v_readlane_b32 s21, v254, 5
	s_waitcnt vmcnt(3)
	v_pk_add_f32 v[108:109], v[108:109], v[136:137]
	s_waitcnt vmcnt(2)
	v_pk_add_f32 v[114:115], v[114:115], v[150:151]
	v_pk_add_f32 v[112:113], v[112:113], v[148:149]
	v_mul_f32_e32 v137, v115, v115
	v_mul_f32_e32 v136, v113, v113
	v_fmac_f32_e32 v136, v112, v112
	v_fmac_f32_e32 v137, v114, v114
	v_add_f32_e32 v136, v136, v137
	v_mul_f32_e32 v137, v109, v109
	v_pk_add_f32 v[110:111], v[110:111], v[138:139]
	v_fmac_f32_e32 v137, v108, v108
	v_add_f32_e32 v136, v136, v137
	v_mul_f32_e32 v137, v111, v111
	global_store_dwordx4 v[130:131], v[112:115], off nt
	global_store_dwordx4 v[130:131], v[108:111], off offset:16 nt
	v_fmac_f32_e32 v137, v110, v110
	v_add_f32_e32 v143, v137, v136
	s_waitcnt vmcnt(3)
	v_pk_add_f32 v[126:127], v[126:127], v[170:171]
	s_waitcnt vmcnt(2)
	v_pk_add_f32 v[122:123], v[122:123], v[174:175]
	v_pk_add_f32 v[120:121], v[120:121], v[172:173]
	v_pk_add_f32 v[124:125], v[124:125], v[168:169]
	global_store_dwordx4 v[130:131], v[120:123], off offset:512 nt
	global_store_dwordx4 v[130:131], v[124:127], off offset:528 nt
	v_mul_f32_e32 v130, v121, v121
	v_mul_f32_e32 v131, v123, v123
	v_fmac_f32_e32 v130, v120, v120
	v_fmac_f32_e32 v131, v122, v122
	v_add_f32_e32 v130, v130, v131
	v_mul_f32_e32 v131, v125, v125
	v_fmac_f32_e32 v131, v124, v124
	v_add_f32_e32 v130, v130, v131
	v_mul_f32_e32 v131, v127, v127
	v_fmac_f32_e32 v131, v126, v126
	v_add_f32_e32 v130, v131, v130
	v_add_f32_e32 v130, v143, v130
	ds_bpermute_b32 v131, v133, v130
	s_waitcnt lgkmcnt(0)
	v_add_f32_e32 v130, v130, v131
	ds_bpermute_b32 v131, v134, v130
	s_and_saveexec_b64 s[16:17], vcc
	s_cbranch_execz .LBB0_712
	s_waitcnt lgkmcnt(0)
	v_add_f32_e32 v130, v130, v131
	ds_write_b32 v135, v130 offset:256
.LBB0_712:
	s_or_b64 exec, exec, s[16:17]
	v_or_b32_e32 v130, 32, v128
	s_waitcnt lgkmcnt(0)
	v_ashrrev_i32_e32 v131, 31, v130
	v_lshlrev_b64 v[130:131], 10, v[130:131]
	v_lshl_add_u64 v[130:131], v[130:131], 0, v[144:145]
	v_lshlrev_b64 v[130:131], 2, v[130:131]
	v_lshl_add_u64 v[140:141], s[14:15], 0, v[130:131]
	global_load_dwordx4 v[136:139], v[140:141], off offset:16 nt
	global_load_dwordx4 v[148:151], v[140:141], off nt
	global_load_dwordx4 v[168:171], v[140:141], off offset:528 nt
	global_load_dwordx4 v[172:175], v[140:141], off offset:512 nt
	v_readlane_b32 s16, v254, 0
	v_readlane_b32 s22, v254, 6
	v_readlane_b32 s23, v254, 7
	v_readlane_b32 s17, v254, 1
	v_readlane_b32 s18, v254, 2
	v_lshl_add_u64 v[130:131], s[22:23], 0, v[130:131]
	v_readlane_b32 s19, v254, 3
	v_readlane_b32 s20, v254, 4
	v_readlane_b32 s21, v254, 5
	s_waitcnt vmcnt(3)
	v_pk_add_f32 v[72:73], v[72:73], v[136:137]
	s_waitcnt vmcnt(2)
	v_pk_add_f32 v[78:79], v[78:79], v[150:151]
	v_pk_add_f32 v[76:77], v[76:77], v[148:149]
	v_mul_f32_e32 v137, v79, v79
	v_mul_f32_e32 v136, v77, v77
	v_fmac_f32_e32 v136, v76, v76
	v_fmac_f32_e32 v137, v78, v78
	v_add_f32_e32 v136, v136, v137
	v_mul_f32_e32 v137, v73, v73
	v_pk_add_f32 v[74:75], v[74:75], v[138:139]
	v_fmac_f32_e32 v137, v72, v72
	v_add_f32_e32 v136, v136, v137
	v_mul_f32_e32 v137, v75, v75
	global_store_dwordx4 v[130:131], v[76:79], off nt
	global_store_dwordx4 v[130:131], v[72:75], off offset:16 nt
	v_fmac_f32_e32 v137, v74, v74
	v_add_f32_e32 v143, v137, v136
	s_waitcnt vmcnt(3)
	v_pk_add_f32 v[82:83], v[82:83], v[170:171]
	s_waitcnt vmcnt(2)
	v_pk_add_f32 v[86:87], v[86:87], v[174:175]
	v_pk_add_f32 v[84:85], v[84:85], v[172:173]
	v_pk_add_f32 v[80:81], v[80:81], v[168:169]
	global_store_dwordx4 v[130:131], v[84:87], off offset:512 nt
	global_store_dwordx4 v[130:131], v[80:83], off offset:528 nt
	v_mul_f32_e32 v130, v85, v85
	v_mul_f32_e32 v131, v87, v87
	v_fmac_f32_e32 v130, v84, v84
	v_fmac_f32_e32 v131, v86, v86
	v_add_f32_e32 v130, v130, v131
	v_mul_f32_e32 v131, v81, v81
	v_fmac_f32_e32 v131, v80, v80
	v_add_f32_e32 v130, v130, v131
	v_mul_f32_e32 v131, v83, v83
	v_fmac_f32_e32 v131, v82, v82
	v_add_f32_e32 v130, v131, v130
	v_add_f32_e32 v130, v143, v130
	ds_bpermute_b32 v131, v133, v130
	s_waitcnt lgkmcnt(0)
	v_add_f32_e32 v130, v130, v131
	ds_bpermute_b32 v131, v134, v130
	s_and_saveexec_b64 s[16:17], vcc
	s_cbranch_execz .LBB0_714
	s_waitcnt lgkmcnt(0)
	v_add_f32_e32 v130, v130, v131
	ds_write_b32 v135, v130 offset:512
.LBB0_714:
	s_or_b64 exec, exec, s[16:17]
	v_or_b32_e32 v130, 48, v128
	s_waitcnt lgkmcnt(0)
	v_ashrrev_i32_e32 v131, 31, v130
	v_lshlrev_b64 v[130:131], 10, v[130:131]
	v_lshl_add_u64 v[130:131], v[130:131], 0, v[144:145]
	v_lshlrev_b64 v[130:131], 2, v[130:131]
	v_lshl_add_u64 v[140:141], s[14:15], 0, v[130:131]
	global_load_dwordx4 v[136:139], v[140:141], off offset:16 nt
	global_load_dwordx4 v[148:151], v[140:141], off nt
	global_load_dwordx4 v[168:171], v[140:141], off offset:528 nt
	global_load_dwordx4 v[172:175], v[140:141], off offset:512 nt
	v_readlane_b32 s16, v254, 0
	v_readlane_b32 s22, v254, 6
	v_readlane_b32 s23, v254, 7
	v_readlane_b32 s17, v254, 1
	v_readlane_b32 s18, v254, 2
	v_lshl_add_u64 v[130:131], s[22:23], 0, v[130:131]
	v_readlane_b32 s19, v254, 3
	v_readlane_b32 s20, v254, 4
	v_readlane_b32 s21, v254, 5
	s_waitcnt vmcnt(3)
	v_pk_add_f32 v[88:89], v[88:89], v[136:137]
	s_waitcnt vmcnt(2)
	v_pk_add_f32 v[94:95], v[94:95], v[150:151]
	v_pk_add_f32 v[92:93], v[92:93], v[148:149]
	v_mul_f32_e32 v137, v95, v95
	v_mul_f32_e32 v136, v93, v93
	v_fmac_f32_e32 v136, v92, v92
	v_fmac_f32_e32 v137, v94, v94
	v_add_f32_e32 v136, v136, v137
	v_mul_f32_e32 v137, v89, v89
	v_pk_add_f32 v[90:91], v[90:91], v[138:139]
	v_fmac_f32_e32 v137, v88, v88
	v_add_f32_e32 v136, v136, v137
	v_mul_f32_e32 v137, v91, v91
	global_store_dwordx4 v[130:131], v[92:95], off nt
	global_store_dwordx4 v[130:131], v[88:91], off offset:16 nt
	v_fmac_f32_e32 v137, v90, v90
	v_add_f32_e32 v143, v137, v136
	s_waitcnt vmcnt(3)
	v_pk_add_f32 v[106:107], v[106:107], v[170:171]
	s_waitcnt vmcnt(2)
	v_pk_add_f32 v[118:119], v[118:119], v[174:175]
	v_pk_add_f32 v[116:117], v[116:117], v[172:173]
	v_pk_add_f32 v[104:105], v[104:105], v[168:169]
	global_store_dwordx4 v[130:131], v[116:119], off offset:512 nt
	global_store_dwordx4 v[130:131], v[104:107], off offset:528 nt
	v_mul_f32_e32 v130, v117, v117
	v_mul_f32_e32 v131, v119, v119
	v_fmac_f32_e32 v130, v116, v116
	v_fmac_f32_e32 v131, v118, v118
	v_add_f32_e32 v130, v130, v131
	v_mul_f32_e32 v131, v105, v105
	v_fmac_f32_e32 v131, v104, v104
	v_add_f32_e32 v130, v130, v131
	v_mul_f32_e32 v131, v107, v107
	v_fmac_f32_e32 v131, v106, v106
	v_add_f32_e32 v130, v131, v130
	v_add_f32_e32 v130, v143, v130
	ds_bpermute_b32 v131, v133, v130
	s_waitcnt lgkmcnt(0)
	v_add_f32_e32 v130, v130, v131
	ds_bpermute_b32 v131, v134, v130
	s_and_saveexec_b64 s[16:17], vcc
	s_cbranch_execz .LBB0_716
	s_waitcnt lgkmcnt(0)
	v_add_f32_e32 v130, v130, v131
	ds_write_b32 v135, v130 offset:768
.LBB0_716:
	s_or_b64 exec, exec, s[16:17]
	s_waitcnt lgkmcnt(0)
	v_lshlrev_b64 v[130:131], 10, v[128:129]
	v_lshl_add_u64 v[130:131], v[130:131], 0, v[144:145]
	v_mov_b64_e32 v[136:137], 0x80000
	v_lshl_add_u64 v[140:141], v[130:131], 2, v[136:137]
	v_lshl_add_u64 v[152:153], s[14:15], 0, v[140:141]
	global_load_dwordx4 v[136:139], v[152:153], off nt
	global_load_dwordx4 v[148:151], v[152:153], off offset:16 nt
	global_load_dwordx4 v[168:171], v[152:153], off offset:512 nt
	global_load_dwordx4 v[172:175], v[152:153], off offset:528 nt
	v_readlane_b32 s16, v254, 0
	v_readlane_b32 s22, v254, 6
	v_readlane_b32 s23, v254, 7
	v_readlane_b32 s17, v254, 1
	v_readlane_b32 s18, v254, 2
	v_lshl_add_u64 v[140:141], s[22:23], 0, v[140:141]
	v_readlane_b32 s19, v254, 3
	v_readlane_b32 s20, v254, 4
	v_readlane_b32 s21, v254, 5
	s_waitcnt vmcnt(3)
	v_pk_add_f32 v[62:63], v[62:63], v[138:139]
	v_pk_add_f32 v[60:61], v[60:61], v[136:137]
	s_waitcnt vmcnt(2)
	v_pk_add_f32 v[58:59], v[58:59], v[150:151]
	v_pk_add_f32 v[56:57], v[56:57], v[148:149]
	global_store_dwordx4 v[140:141], v[60:63], off nt
	global_store_dwordx4 v[140:141], v[56:59], off offset:16 nt
	v_mul_f32_e32 v143, v61, v61
	v_mul_f32_e32 v147, v63, v63
	v_mul_f32_e32 v152, v57, v57
	v_fmac_f32_e32 v143, v60, v60
	v_fmac_f32_e32 v147, v62, v62
	v_mul_f32_e32 v153, v59, v59
	v_fmac_f32_e32 v152, v56, v56
	v_add_f32_e32 v143, v143, v147
	v_fmac_f32_e32 v153, v58, v58
	v_add_f32_e32 v143, v143, v152
	v_add_f32_e32 v143, v153, v143
	s_waitcnt vmcnt(3)
	v_pk_add_f32 v[54:55], v[54:55], v[170:171]
	v_pk_add_f32 v[52:53], v[52:53], v[168:169]
	s_waitcnt vmcnt(2)
	v_pk_add_f32 v[48:49], v[48:49], v[172:173]
	v_mul_f32_e32 v136, v53, v53
	v_mul_f32_e32 v137, v55, v55
	v_pk_add_f32 v[50:51], v[50:51], v[174:175]
	v_mul_f32_e32 v138, v49, v49
	v_fmac_f32_e32 v136, v52, v52
	v_fmac_f32_e32 v137, v54, v54
	v_mul_f32_e32 v139, v51, v51
	v_fmac_f32_e32 v138, v48, v48
	v_add_f32_e32 v136, v136, v137
	v_add_f32_e32 v136, v136, v138
	v_fmac_f32_e32 v139, v50, v50
	v_add_f32_e32 v136, v139, v136
	v_add_f32_e32 v136, v143, v136
	ds_bpermute_b32 v137, v133, v136
	v_add_u32_e32 v148, 0x80, v146
	global_store_dwordx4 v[140:141], v[52:55], off offset:512 nt
	global_store_dwordx4 v[140:141], v[48:51], off offset:528 nt
	s_waitcnt lgkmcnt(0)
	v_add_f32_e32 v136, v136, v137
	ds_bpermute_b32 v137, v134, v136
	s_and_saveexec_b64 s[16:17], vcc
	s_cbranch_execz .LBB0_718
	v_lshl_add_u32 v138, v148, 4, s4
	s_waitcnt lgkmcnt(0)
	v_add_f32_e32 v136, v136, v137
	ds_write_b32 v138, v136
.LBB0_718:
	s_or_b64 exec, exec, s[16:17]
	s_waitcnt lgkmcnt(0)
	v_mov_b64_e32 v[136:137], 0x90000
	v_lshl_add_u64 v[130:131], v[130:131], 2, v[136:137]
	v_lshl_add_u64 v[140:141], s[14:15], 0, v[130:131]
	global_load_dwordx4 v[136:139], v[140:141], off offset:16 nt
	global_load_dwordx4 v[150:153], v[140:141], off nt
	global_load_dwordx4 v[168:171], v[140:141], off offset:528 nt
	global_load_dwordx4 v[172:175], v[140:141], off offset:512 nt
	v_readlane_b32 s16, v254, 0
	v_readlane_b32 s22, v254, 6
	v_readlane_b32 s23, v254, 7
	v_readlane_b32 s17, v254, 1
	v_readlane_b32 s18, v254, 2
	v_lshl_add_u64 v[130:131], s[22:23], 0, v[130:131]
	v_readlane_b32 s19, v254, 3
	v_readlane_b32 s20, v254, 4
	v_readlane_b32 s21, v254, 5
	s_waitcnt vmcnt(3)
	v_pk_add_f32 v[40:41], v[40:41], v[136:137]
	s_waitcnt vmcnt(2)
	v_pk_add_f32 v[46:47], v[46:47], v[152:153]
	v_pk_add_f32 v[44:45], v[44:45], v[150:151]
	v_mul_f32_e32 v137, v47, v47
	v_mul_f32_e32 v136, v45, v45
	v_fmac_f32_e32 v136, v44, v44
	v_fmac_f32_e32 v137, v46, v46
	v_add_f32_e32 v136, v136, v137
	v_mul_f32_e32 v137, v41, v41
	v_pk_add_f32 v[42:43], v[42:43], v[138:139]
	v_fmac_f32_e32 v137, v40, v40
	v_add_f32_e32 v136, v136, v137
	v_mul_f32_e32 v137, v43, v43
	global_store_dwordx4 v[130:131], v[44:47], off nt
	global_store_dwordx4 v[130:131], v[40:43], off offset:16 nt
	v_fmac_f32_e32 v137, v42, v42
	v_add_f32_e32 v143, v137, v136
	s_waitcnt vmcnt(3)
	v_pk_add_f32 v[34:35], v[34:35], v[170:171]
	s_waitcnt vmcnt(2)
	v_pk_add_f32 v[38:39], v[38:39], v[174:175]
	v_pk_add_f32 v[36:37], v[36:37], v[172:173]
	v_pk_add_f32 v[32:33], v[32:33], v[168:169]
	global_store_dwordx4 v[130:131], v[36:39], off offset:512 nt
	global_store_dwordx4 v[130:131], v[32:35], off offset:528 nt
	v_mul_f32_e32 v130, v37, v37
	v_mul_f32_e32 v131, v39, v39
	v_fmac_f32_e32 v130, v36, v36
	v_fmac_f32_e32 v131, v38, v38
	v_add_f32_e32 v130, v130, v131
	v_mul_f32_e32 v131, v33, v33
	v_fmac_f32_e32 v131, v32, v32
	v_add_f32_e32 v130, v130, v131
	v_mul_f32_e32 v131, v35, v35
	v_fmac_f32_e32 v131, v34, v34
	v_add_f32_e32 v130, v131, v130
	v_add_f32_e32 v130, v143, v130
	ds_bpermute_b32 v131, v133, v130
	s_waitcnt lgkmcnt(0)
	v_add_f32_e32 v130, v130, v131
	ds_bpermute_b32 v131, v134, v130
	s_and_saveexec_b64 s[16:17], vcc
	s_cbranch_execz .LBB0_720
	s_waitcnt lgkmcnt(0)
	v_add_f32_e32 v130, v130, v131
	ds_write_b32 v135, v130 offset:2304
.LBB0_720:
	s_or_b64 exec, exec, s[16:17]
	v_lshlrev_b64 v[128:129], 10, v[128:129]
	v_lshl_add_u64 v[128:129], v[128:129], 0, v[144:145]
	s_waitcnt lgkmcnt(0)
	v_mov_b64_e32 v[130:131], 0xa0000
	v_lshl_add_u64 v[130:131], v[128:129], 2, v[130:131]
	v_lshl_add_u64 v[140:141], s[14:15], 0, v[130:131]
	global_load_dwordx4 v[136:139], v[140:141], off offset:16 nt
	global_load_dwordx4 v[150:153], v[140:141], off nt
	global_load_dwordx4 v[168:171], v[140:141], off offset:528 nt
	global_load_dwordx4 v[172:175], v[140:141], off offset:512 nt
	v_readlane_b32 s16, v254, 0
	v_readlane_b32 s22, v254, 6
	v_readlane_b32 s23, v254, 7
	v_readlane_b32 s17, v254, 1
	v_readlane_b32 s18, v254, 2
	v_lshl_add_u64 v[130:131], s[22:23], 0, v[130:131]
	v_readlane_b32 s19, v254, 3
	v_readlane_b32 s20, v254, 4
	v_readlane_b32 s21, v254, 5
	s_waitcnt vmcnt(3)
	v_pk_add_f32 v[24:25], v[24:25], v[136:137]
	s_waitcnt vmcnt(2)
	v_pk_add_f32 v[30:31], v[30:31], v[152:153]
	v_pk_add_f32 v[28:29], v[28:29], v[150:151]
	v_mul_f32_e32 v137, v31, v31
	v_mul_f32_e32 v136, v29, v29
	v_fmac_f32_e32 v136, v28, v28
	v_fmac_f32_e32 v137, v30, v30
	v_add_f32_e32 v136, v136, v137
	v_mul_f32_e32 v137, v25, v25
	v_pk_add_f32 v[26:27], v[26:27], v[138:139]
	v_fmac_f32_e32 v137, v24, v24
	v_add_f32_e32 v136, v136, v137
	v_mul_f32_e32 v137, v27, v27
	global_store_dwordx4 v[130:131], v[28:31], off nt
	global_store_dwordx4 v[130:131], v[24:27], off offset:16 nt
	v_fmac_f32_e32 v137, v26, v26
	v_add_f32_e32 v143, v137, v136
	s_waitcnt vmcnt(3)
	v_pk_add_f32 v[18:19], v[18:19], v[170:171]
	s_waitcnt vmcnt(2)
	v_pk_add_f32 v[22:23], v[22:23], v[174:175]
	v_pk_add_f32 v[20:21], v[20:21], v[172:173]
	v_pk_add_f32 v[16:17], v[16:17], v[168:169]
	global_store_dwordx4 v[130:131], v[20:23], off offset:512 nt
	global_store_dwordx4 v[130:131], v[16:19], off offset:528 nt
	v_mul_f32_e32 v130, v21, v21
	v_mul_f32_e32 v131, v23, v23
	v_fmac_f32_e32 v130, v20, v20
	v_fmac_f32_e32 v131, v22, v22
	v_add_f32_e32 v130, v130, v131
	v_mul_f32_e32 v131, v17, v17
	v_fmac_f32_e32 v131, v16, v16
	v_add_f32_e32 v130, v130, v131
	v_mul_f32_e32 v131, v19, v19
	v_fmac_f32_e32 v131, v18, v18
	v_add_f32_e32 v130, v131, v130
	v_add_f32_e32 v130, v143, v130
	ds_bpermute_b32 v131, v133, v130
	s_waitcnt lgkmcnt(0)
	v_add_f32_e32 v130, v130, v131
	ds_bpermute_b32 v131, v134, v130
	s_and_saveexec_b64 s[16:17], vcc
	s_cbranch_execz .LBB0_722
	s_waitcnt lgkmcnt(0)
	v_add_f32_e32 v130, v130, v131
	ds_write_b32 v135, v130 offset:2560
.LBB0_722:
	s_or_b64 exec, exec, s[16:17]
	s_waitcnt lgkmcnt(0)
	v_mov_b64_e32 v[130:131], 0xb0000
	v_lshl_add_u64 v[140:141], v[128:129], 2, v[130:131]
	v_lshl_add_u64 v[150:151], s[14:15], 0, v[140:141]
	global_load_dwordx4 v[128:131], v[150:151], off offset:16 nt
	global_load_dwordx4 v[136:139], v[150:151], off nt
	global_load_dwordx4 v[168:171], v[150:151], off offset:528 nt
	global_load_dwordx4 v[172:175], v[150:151], off offset:512 nt
	v_readlane_b32 s16, v254, 0
	v_readlane_b32 s22, v254, 6
	v_readlane_b32 s23, v254, 7
	v_readlane_b32 s17, v254, 1
	v_readlane_b32 s18, v254, 2
	v_lshl_add_u64 v[140:141], s[22:23], 0, v[140:141]
	v_readlane_b32 s19, v254, 3
	v_readlane_b32 s20, v254, 4
	v_readlane_b32 s21, v254, 5
	s_waitcnt vmcnt(3)
	v_pk_add_f32 v[8:9], v[8:9], v[128:129]
	s_waitcnt vmcnt(2)
	v_pk_add_f32 v[14:15], v[14:15], v[138:139]
	v_pk_add_f32 v[12:13], v[12:13], v[136:137]
	v_mul_f32_e32 v129, v15, v15
	v_mul_f32_e32 v128, v13, v13
	v_fmac_f32_e32 v128, v12, v12
	v_fmac_f32_e32 v129, v14, v14
	v_add_f32_e32 v128, v128, v129
	v_mul_f32_e32 v129, v9, v9
	v_pk_add_f32 v[10:11], v[10:11], v[130:131]
	v_fmac_f32_e32 v129, v8, v8
	v_add_f32_e32 v128, v128, v129
	v_mul_f32_e32 v129, v11, v11
	global_store_dwordx4 v[140:141], v[12:15], off nt
	global_store_dwordx4 v[140:141], v[8:11], off offset:16 nt
	v_fmac_f32_e32 v129, v10, v10
	v_add_f32_e32 v143, v129, v128
	s_waitcnt vmcnt(3)
	v_pk_add_f32 v[0:1], v[0:1], v[168:169]
	s_waitcnt vmcnt(2)
	v_pk_add_f32 v[6:7], v[6:7], v[174:175]
	v_pk_add_f32 v[4:5], v[4:5], v[172:173]
	v_mul_f32_e32 v129, v7, v7
	v_mul_f32_e32 v128, v5, v5
	v_fmac_f32_e32 v128, v4, v4
	v_fmac_f32_e32 v129, v6, v6
	v_add_f32_e32 v128, v128, v129
	v_mul_f32_e32 v129, v1, v1
	v_pk_add_f32 v[2:3], v[2:3], v[170:171]
	v_fmac_f32_e32 v129, v0, v0
	v_add_f32_e32 v128, v128, v129
	v_mul_f32_e32 v129, v3, v3
	v_fmac_f32_e32 v129, v2, v2
	v_add_f32_e32 v128, v129, v128
	v_add_f32_e32 v128, v143, v128
	ds_bpermute_b32 v129, v133, v128
	global_store_dwordx4 v[140:141], v[4:7], off offset:512 nt
	global_store_dwordx4 v[140:141], v[0:3], off offset:528 nt
	s_waitcnt lgkmcnt(0)
	v_add_f32_e32 v128, v128, v129
	ds_bpermute_b32 v129, v134, v128
	s_and_saveexec_b64 s[14:15], vcc
	s_cbranch_execz .LBB0_724
	s_waitcnt lgkmcnt(0)
	v_add_f32_e32 v128, v128, v129
	ds_write_b32 v135, v128 offset:2816

.LBB0_986:
	v_and_b32_e32 v131, 64, v227
	s_add_u32 s6, s14, 0xdb00000
	v_xor_b32_e32 v130, 16, v227
	v_add_u32_e32 v131, 64, v131
	s_addc_u32 s7, s15, 0
	s_lshl_b32 s19, s18, 8
	v_cmp_lt_i32_e32 vcc, v130, v131
	s_add_i32 s1, s19, s4
	s_lshl_b32 s0, s3, 5
	v_cndmask_b32_e32 v130, v227, v130, vcc
	v_or_b32_e32 v138, s1, v142
	s_lshl_b32 s1, s42, 8
	v_lshlrev_b32_e32 v157, 2, v130
	v_xor_b32_e32 v130, 32, v227
	v_lshrrev_b32_e32 v128, 1, v155
	s_or_b32 s0, s1, s0
	v_cmp_lt_i32_e32 vcc, v130, v131
	v_and_or_b32 v128, v128, 24, s0
	v_ashrrev_i32_e32 v139, 31, v138
	v_cndmask_b32_e32 v130, v227, v130, vcc
	v_ashrrev_i32_e32 v129, 31, v128
	v_lshlrev_b32_e32 v158, 2, v130
	v_lshlrev_b64 v[130:131], 10, v[138:139]
	v_lshl_add_u64 v[130:131], v[130:131], 0, v[128:129]
	v_lshlrev_b64 v[130:131], 1, v[130:131]
	v_lshl_add_u64 v[148:149], s[16:17], 0, v[130:131]
	v_lshl_add_u64 v[150:151], s[6:7], 0, v[130:131]
	s_barrier
	global_load_dwordx4 v[134:137], v[148:149], off
	global_load_dwordx4 v[140:143], v[150:151], off
	global_load_dwordx4 v[168:171], v[148:149], off offset:256
	global_load_dwordx4 v[172:175], v[150:151], off offset:256
	v_mul_f32_e32 v124, 0xbfb8aa3b, v124
	v_mul_f32_e32 v125, 0xbfb8aa3b, v125
	v_exp_f32_e32 v124, v124
	v_mul_f32_e32 v120, 0xbfb8aa3b, v120
	v_exp_f32_e32 v125, v125
	v_mul_f32_e32 v121, 0xbfb8aa3b, v121
	v_exp_f32_e32 v120, v120
	v_exp_f32_e32 v121, v121
	v_add_f32_e32 v124, 1.0, v124
	v_add_f32_e32 v125, 1.0, v125
	v_rcp_f32_e32 v124, v124
	v_add_f32_e32 v120, 1.0, v120
	v_rcp_f32_e32 v125, v125
	v_add_f32_e32 v121, 1.0, v121
	v_rcp_f32_e32 v120, v120
	v_rcp_f32_e32 v121, v121
	v_mul_f32_e32 v116, 0xbfb8aa3b, v116
	v_mul_f32_e32 v117, 0xbfb8aa3b, v117
	v_mul_f32_e32 v118, 0xbfb8aa3b, v118
	v_mul_f32_e32 v119, 0xbfb8aa3b, v119
	v_exp_f32_e32 v116, v116
	v_exp_f32_e32 v117, v117
	v_exp_f32_e32 v118, v118
	v_mul_f32_e32 v114, 0xbfb8aa3b, v114
	v_exp_f32_e32 v119, v119
	v_mul_f32_e32 v115, 0xbfb8aa3b, v115
	v_mul_f32_e32 v112, 0xbfb8aa3b, v112
	v_mul_f32_e32 v113, 0xbfb8aa3b, v113
	v_exp_f32_e32 v114, v114
	v_exp_f32_e32 v115, v115
	v_exp_f32_e32 v112, v112
	v_exp_f32_e32 v113, v113
	v_add_f32_e32 v116, 1.0, v116
	v_add_f32_e32 v117, 1.0, v117
	v_add_f32_e32 v118, 1.0, v118
	v_add_f32_e32 v119, 1.0, v119
	v_rcp_f32_e32 v116, v116
	v_rcp_f32_e32 v117, v117
	v_rcp_f32_e32 v118, v118
	v_add_f32_e32 v114, 1.0, v114
	v_rcp_f32_e32 v119, v119
	v_add_f32_e32 v115, 1.0, v115
	v_add_f32_e32 v112, 1.0, v112
	v_add_f32_e32 v113, 1.0, v113
	v_rcp_f32_e32 v114, v114
	v_rcp_f32_e32 v115, v115
	v_rcp_f32_e32 v112, v112
	v_rcp_f32_e32 v113, v113
	s_lshl_b32 s0, s3, 2
	v_and_b32_e32 v156, 63, v155
	s_add_i32 s0, s0, 0
	v_cmp_gt_u32_e32 vcc, 16, v156
	v_lshl_add_u32 v159, v154, 4, s0
	s_waitcnt vmcnt(2)
	v_lshlrev_b32_e32 v130, 16, v134
	v_and_b32_e32 v131, 0xffff0000, v134
	v_lshlrev_b32_e32 v132, 16, v140
	v_and_b32_e32 v133, 0xffff0000, v140
	v_pk_fma_f32 v[130:131], v[124:125], v[132:133], v[130:131]
	v_lshlrev_b32_e32 v124, 16, v136
	v_and_b32_e32 v125, 0xffff0000, v136
	v_lshlrev_b32_e32 v132, 16, v142
	v_and_b32_e32 v133, 0xffff0000, v142
	v_pk_fma_f32 v[132:133], v[120:121], v[132:133], v[124:125]
	v_mul_f32_e32 v121, 0xbfb8aa3b, v122
	v_exp_f32_e32 v121, v121
	v_mul_f32_e32 v120, 0xbfb8aa3b, v126
	v_exp_f32_e32 v120, v120
	v_lshlrev_b32_e32 v124, 16, v135
	v_add_f32_e32 v121, 1.0, v121
	v_rcp_f32_e32 v122, v121
	v_mul_f32_e32 v121, 0xbfb8aa3b, v127
	v_exp_f32_e32 v121, v121
	v_add_f32_e32 v120, 1.0, v120
	v_rcp_f32_e32 v120, v120
	v_and_b32_e32 v125, 0xffff0000, v135
	v_add_f32_e32 v121, 1.0, v121
	v_rcp_f32_e32 v121, v121
	v_lshlrev_b32_e32 v126, 16, v141
	v_and_b32_e32 v127, 0xffff0000, v141
	v_pk_mul_f32 v[140:141], v[130:131], v[130:131]
	v_pk_fma_f32 v[134:135], v[120:121], v[126:127], v[124:125]
	v_mul_f32_e32 v120, 0xbfb8aa3b, v123
	v_exp_f32_e32 v120, v120
	v_and_b32_e32 v121, 0xffff0000, v137
	v_lshlrev_b32_e32 v124, 16, v143
	v_and_b32_e32 v125, 0xffff0000, v143
	v_add_f32_e32 v120, 1.0, v120
	v_rcp_f32_e32 v123, v120
	v_lshlrev_b32_e32 v120, 16, v137
	v_pk_mul_f32 v[144:145], v[134:135], v[134:135]
	v_pk_mul_f32 v[142:143], v[132:133], v[132:133]
	v_pk_fma_f32 v[136:137], v[122:123], v[124:125], v[120:121]
	v_pk_mul_f32 v[146:147], v[136:137], v[136:137]
	s_waitcnt vmcnt(1)
	v_lshlrev_b32_e32 v148, 16, v168
	v_and_b32_e32 v149, 0xffff0000, v168
	s_waitcnt vmcnt(0)
	v_lshlrev_b32_e32 v150, 16, v172
	v_and_b32_e32 v151, 0xffff0000, v172
	v_lshlrev_b32_e32 v124, 16, v169
	v_and_b32_e32 v125, 0xffff0000, v169
	v_lshlrev_b32_e32 v120, 16, v173
	v_and_b32_e32 v121, 0xffff0000, v173
	v_pk_fma_f32 v[116:117], v[116:117], v[150:151], v[148:149]
	v_lshlrev_b32_e32 v150, 16, v174
	v_and_b32_e32 v151, 0xffff0000, v174
	v_pk_fma_f32 v[118:119], v[118:119], v[120:121], v[124:125]
	v_lshlrev_b32_e32 v120, 16, v171
	v_and_b32_e32 v121, 0xffff0000, v171
	v_lshlrev_b32_e32 v122, 16, v175
	v_and_b32_e32 v123, 0xffff0000, v175
	v_lshlrev_b32_e32 v148, 16, v170
	v_and_b32_e32 v149, 0xffff0000, v170
	v_pk_fma_f32 v[126:127], v[114:115], v[122:123], v[120:121]
	v_pk_mul_f32 v[114:115], v[116:117], v[116:117]
	v_pk_mul_f32 v[120:121], v[118:119], v[118:119]
	v_pk_fma_f32 v[112:113], v[112:113], v[150:151], v[148:149]
	v_add_f32_e32 v120, v120, v121
	v_add_f32_e32 v114, v114, v115
	v_pk_mul_f32 v[122:123], v[112:113], v[112:113]
	v_add_f32_e32 v114, v114, v120
	v_add_f32_e32 v120, v144, v145
	v_add_f32_e32 v121, v140, v141
	v_pk_mul_f32 v[124:125], v[126:127], v[126:127]
	v_add_f32_e32 v115, v122, v123
	v_add_f32_e32 v120, v121, v120
	v_add_f32_e32 v121, v142, v143
	v_add_f32_e32 v124, v124, v125
	v_add_f32_e32 v114, v115, v114
	v_add_f32_e32 v115, v146, v147
	v_add_f32_e32 v120, v121, v120
	v_add_f32_e32 v114, v124, v114
	v_add_f32_e32 v115, v115, v120
	v_add_f32_e32 v114, v115, v114
	ds_bpermute_b32 v115, v157, v114
	s_waitcnt lgkmcnt(0)
	v_add_f32_e32 v114, v114, v115
	ds_bpermute_b32 v115, v158, v114
	s_and_saveexec_b64 s[8:9], vcc
	s_cbranch_execz .LBB0_988
	s_waitcnt lgkmcnt(0)
	v_add_f32_e32 v114, v114, v115
	ds_write_b32 v159, v114
.LBB0_988:
	s_or_b64 exec, exec, s[8:9]
	v_or_b32_e32 v114, 16, v138
	s_waitcnt lgkmcnt(0)
	v_ashrrev_i32_e32 v115, 31, v114
	v_lshlrev_b64 v[114:115], 10, v[114:115]
	v_lshl_add_u64 v[114:115], v[114:115], 0, v[128:129]
	v_lshlrev_b64 v[114:115], 1, v[114:115]
	v_lshl_add_u64 v[148:149], s[16:17], 0, v[114:115]
	v_lshl_add_u64 v[150:151], s[6:7], 0, v[114:115]
	global_load_dwordx4 v[122:125], v[148:149], off
	global_load_dwordx4 v[140:143], v[150:151], off
	global_load_dwordx4 v[168:171], v[148:149], off offset:256
	global_load_dwordx4 v[172:175], v[150:151], off offset:256
	v_mul_f32_e32 v108, 0xbfb8aa3b, v108
	v_mul_f32_e32 v109, 0xbfb8aa3b, v109
	v_exp_f32_e32 v108, v108
	v_mul_f32_e32 v104, 0xbfb8aa3b, v104
	v_exp_f32_e32 v109, v109
	v_mul_f32_e32 v105, 0xbfb8aa3b, v105
	v_exp_f32_e32 v104, v104
	v_exp_f32_e32 v105, v105
	v_add_f32_e32 v108, 1.0, v108
	v_add_f32_e32 v109, 1.0, v109
	v_rcp_f32_e32 v108, v108
	v_add_f32_e32 v104, 1.0, v104
	v_rcp_f32_e32 v109, v109
	v_add_f32_e32 v105, 1.0, v105
	v_rcp_f32_e32 v104, v104
	v_rcp_f32_e32 v105, v105
	v_mul_f32_e32 v100, 0xbfb8aa3b, v100
	v_mul_f32_e32 v101, 0xbfb8aa3b, v101
	v_mul_f32_e32 v102, 0xbfb8aa3b, v102
	v_mul_f32_e32 v103, 0xbfb8aa3b, v103
	v_exp_f32_e32 v100, v100
	v_exp_f32_e32 v101, v101
	v_exp_f32_e32 v102, v102
	v_mul_f32_e32 v98, 0xbfb8aa3b, v98
	v_exp_f32_e32 v103, v103
	v_mul_f32_e32 v99, 0xbfb8aa3b, v99
	v_mul_f32_e32 v96, 0xbfb8aa3b, v96
	v_mul_f32_e32 v97, 0xbfb8aa3b, v97
	v_exp_f32_e32 v98, v98
	v_exp_f32_e32 v99, v99
	v_exp_f32_e32 v96, v96
	v_exp_f32_e32 v97, v97
	v_add_f32_e32 v100, 1.0, v100
	v_add_f32_e32 v101, 1.0, v101
	v_add_f32_e32 v102, 1.0, v102
	v_add_f32_e32 v103, 1.0, v103
	v_rcp_f32_e32 v100, v100
	v_rcp_f32_e32 v101, v101
	v_rcp_f32_e32 v102, v102
	v_add_f32_e32 v98, 1.0, v98
	v_rcp_f32_e32 v103, v103
	v_add_f32_e32 v99, 1.0, v99
	v_add_f32_e32 v96, 1.0, v96
	v_add_f32_e32 v97, 1.0, v97
	v_rcp_f32_e32 v98, v98
	v_rcp_f32_e32 v99, v99
	v_rcp_f32_e32 v96, v96
	v_rcp_f32_e32 v97, v97
	s_waitcnt vmcnt(3)
	v_lshlrev_b32_e32 v114, 16, v122
	v_and_b32_e32 v115, 0xffff0000, v122
	s_waitcnt vmcnt(2)
	v_lshlrev_b32_e32 v120, 16, v140
	v_and_b32_e32 v121, 0xffff0000, v140
	v_pk_fma_f32 v[114:115], v[108:109], v[120:121], v[114:115]
	v_lshlrev_b32_e32 v108, 16, v124
	v_and_b32_e32 v109, 0xffff0000, v124
	v_lshlrev_b32_e32 v120, 16, v142
	v_and_b32_e32 v121, 0xffff0000, v142
	v_pk_fma_f32 v[120:121], v[104:105], v[120:121], v[108:109]
	v_mul_f32_e32 v105, 0xbfb8aa3b, v106
	v_exp_f32_e32 v105, v105
	v_mul_f32_e32 v104, 0xbfb8aa3b, v110
	v_exp_f32_e32 v104, v104
	v_lshlrev_b32_e32 v108, 16, v123
	v_add_f32_e32 v105, 1.0, v105
	v_rcp_f32_e32 v106, v105
	v_mul_f32_e32 v105, 0xbfb8aa3b, v111
	v_exp_f32_e32 v105, v105
	v_add_f32_e32 v104, 1.0, v104
	v_rcp_f32_e32 v104, v104
	v_and_b32_e32 v109, 0xffff0000, v123
	v_add_f32_e32 v105, 1.0, v105
	v_rcp_f32_e32 v105, v105
	v_lshlrev_b32_e32 v110, 16, v141
	v_and_b32_e32 v111, 0xffff0000, v141
	v_pk_mul_f32 v[140:141], v[114:115], v[114:115]
	v_pk_fma_f32 v[122:123], v[104:105], v[110:111], v[108:109]
	v_mul_f32_e32 v104, 0xbfb8aa3b, v107
	v_exp_f32_e32 v104, v104
	v_and_b32_e32 v105, 0xffff0000, v125
	v_lshlrev_b32_e32 v108, 16, v143
	v_and_b32_e32 v109, 0xffff0000, v143
	v_add_f32_e32 v104, 1.0, v104
	v_rcp_f32_e32 v107, v104
	v_lshlrev_b32_e32 v104, 16, v125
	v_pk_mul_f32 v[144:145], v[122:123], v[122:123]
	v_pk_mul_f32 v[142:143], v[120:121], v[120:121]
	v_pk_fma_f32 v[124:125], v[106:107], v[108:109], v[104:105]
	v_pk_mul_f32 v[146:147], v[124:125], v[124:125]
	s_waitcnt vmcnt(1)
	v_lshlrev_b32_e32 v148, 16, v168
	v_and_b32_e32 v149, 0xffff0000, v168
	s_waitcnt vmcnt(0)
	v_lshlrev_b32_e32 v150, 16, v172
	v_and_b32_e32 v151, 0xffff0000, v172
	v_lshlrev_b32_e32 v108, 16, v169
	v_and_b32_e32 v109, 0xffff0000, v169
	v_lshlrev_b32_e32 v104, 16, v173
	v_and_b32_e32 v105, 0xffff0000, v173
	v_pk_fma_f32 v[100:101], v[100:101], v[150:151], v[148:149]
	v_pk_fma_f32 v[108:109], v[102:103], v[104:105], v[108:109]
	v_lshlrev_b32_e32 v102, 16, v171
	v_and_b32_e32 v103, 0xffff0000, v171
	v_lshlrev_b32_e32 v104, 16, v175
	v_and_b32_e32 v105, 0xffff0000, v175
	v_lshlrev_b32_e32 v148, 16, v170
	v_and_b32_e32 v149, 0xffff0000, v170
	v_lshlrev_b32_e32 v150, 16, v174
	v_and_b32_e32 v151, 0xffff0000, v174
	v_pk_fma_f32 v[110:111], v[98:99], v[104:105], v[102:103]
	v_pk_mul_f32 v[98:99], v[100:101], v[100:101]
	v_pk_mul_f32 v[102:103], v[108:109], v[108:109]
	v_pk_fma_f32 v[96:97], v[96:97], v[150:151], v[148:149]
	v_add_f32_e32 v102, v102, v103
	v_add_f32_e32 v98, v98, v99
	v_pk_mul_f32 v[104:105], v[96:97], v[96:97]
	v_add_f32_e32 v98, v98, v102
	v_add_f32_e32 v102, v144, v145
	v_add_f32_e32 v103, v140, v141
	v_pk_mul_f32 v[106:107], v[110:111], v[110:111]
	v_add_f32_e32 v99, v104, v105
	v_add_f32_e32 v102, v103, v102
	v_add_f32_e32 v103, v142, v143
	v_add_f32_e32 v106, v106, v107
	v_add_f32_e32 v98, v99, v98
	v_add_f32_e32 v99, v146, v147
	v_add_f32_e32 v102, v103, v102
	v_add_f32_e32 v98, v106, v98
	v_add_f32_e32 v99, v99, v102
	v_add_f32_e32 v98, v99, v98
	ds_bpermute_b32 v99, v157, v98
	s_waitcnt lgkmcnt(0)
	v_add_f32_e32 v98, v98, v99
	ds_bpermute_b32 v99, v158, v98
	s_and_saveexec_b64 s[8:9], vcc
	s_cbranch_execz .LBB0_990
	s_waitcnt lgkmcnt(0)
	v_add_f32_e32 v98, v98, v99
	ds_write_b32 v159, v98 offset:256
.LBB0_990:
	s_or_b64 exec, exec, s[8:9]
	v_or_b32_e32 v98, 32, v138
	s_waitcnt lgkmcnt(0)
	v_ashrrev_i32_e32 v99, 31, v98
	v_lshlrev_b64 v[98:99], 10, v[98:99]
	v_lshl_add_u64 v[98:99], v[98:99], 0, v[128:129]
	v_lshlrev_b64 v[98:99], 1, v[98:99]
	v_lshl_add_u64 v[140:141], s[16:17], 0, v[98:99]
	v_lshl_add_u64 v[150:151], s[6:7], 0, v[98:99]
	global_load_dwordx4 v[104:107], v[140:141], off
	global_load_dwordx4 v[142:145], v[150:151], off
	global_load_dwordx4 v[168:171], v[140:141], off offset:256
	global_load_dwordx4 v[172:175], v[150:151], off offset:256
	v_mul_f32_e32 v92, 0xbfb8aa3b, v92
	v_mul_f32_e32 v93, 0xbfb8aa3b, v93
	v_exp_f32_e32 v92, v92
	v_mul_f32_e32 v88, 0xbfb8aa3b, v88
	v_exp_f32_e32 v93, v93
	v_mul_f32_e32 v89, 0xbfb8aa3b, v89
	v_exp_f32_e32 v88, v88
	v_exp_f32_e32 v89, v89
	v_add_f32_e32 v92, 1.0, v92
	v_add_f32_e32 v93, 1.0, v93
	v_rcp_f32_e32 v92, v92
	v_add_f32_e32 v88, 1.0, v88
	v_rcp_f32_e32 v93, v93
	v_add_f32_e32 v89, 1.0, v89
	v_rcp_f32_e32 v88, v88
	v_rcp_f32_e32 v89, v89
	v_mul_f32_e32 v84, 0xbfb8aa3b, v84
	v_mul_f32_e32 v85, 0xbfb8aa3b, v85
	v_exp_f32_e32 v84, v84
	v_mul_f32_e32 v80, 0xbfb8aa3b, v80
	v_exp_f32_e32 v85, v85
	v_mul_f32_e32 v81, 0xbfb8aa3b, v81
	v_exp_f32_e32 v80, v80
	v_exp_f32_e32 v81, v81
	v_add_f32_e32 v84, 1.0, v84
	v_add_f32_e32 v85, 1.0, v85
	v_rcp_f32_e32 v84, v84
	v_add_f32_e32 v80, 1.0, v80
	v_rcp_f32_e32 v85, v85
	v_add_f32_e32 v81, 1.0, v81
	v_rcp_f32_e32 v80, v80
	v_rcp_f32_e32 v81, v81
	s_waitcnt vmcnt(3)
	v_lshlrev_b32_e32 v98, 16, v104
	v_and_b32_e32 v99, 0xffff0000, v104
	s_waitcnt vmcnt(2)
	v_lshlrev_b32_e32 v102, 16, v142
	v_and_b32_e32 v103, 0xffff0000, v142
	v_pk_fma_f32 v[98:99], v[92:93], v[102:103], v[98:99]
	v_lshlrev_b32_e32 v92, 16, v106
	v_and_b32_e32 v93, 0xffff0000, v106
	v_lshlrev_b32_e32 v102, 16, v144
	v_and_b32_e32 v103, 0xffff0000, v144
	v_pk_fma_f32 v[102:103], v[88:89], v[102:103], v[92:93]
	v_mul_f32_e32 v89, 0xbfb8aa3b, v90
	v_exp_f32_e32 v89, v89
	v_mul_f32_e32 v88, 0xbfb8aa3b, v94
	v_exp_f32_e32 v88, v88
	v_lshlrev_b32_e32 v92, 16, v105
	v_add_f32_e32 v89, 1.0, v89
	v_rcp_f32_e32 v90, v89
	v_mul_f32_e32 v89, 0xbfb8aa3b, v95
	v_exp_f32_e32 v89, v89
	v_add_f32_e32 v88, 1.0, v88
	v_rcp_f32_e32 v88, v88
	v_and_b32_e32 v93, 0xffff0000, v105
	v_add_f32_e32 v89, 1.0, v89
	v_rcp_f32_e32 v89, v89
	v_lshlrev_b32_e32 v94, 16, v143
	v_and_b32_e32 v95, 0xffff0000, v143
	v_pk_mul_f32 v[142:143], v[98:99], v[98:99]
	v_pk_fma_f32 v[104:105], v[88:89], v[94:95], v[92:93]
	v_mul_f32_e32 v88, 0xbfb8aa3b, v91
	v_exp_f32_e32 v88, v88
	v_and_b32_e32 v89, 0xffff0000, v107
	v_lshlrev_b32_e32 v92, 16, v145
	v_and_b32_e32 v93, 0xffff0000, v145
	v_add_f32_e32 v88, 1.0, v88
	v_rcp_f32_e32 v91, v88
	v_lshlrev_b32_e32 v88, 16, v107
	v_pk_mul_f32 v[146:147], v[104:105], v[104:105]
	v_pk_mul_f32 v[144:145], v[102:103], v[102:103]
	v_pk_fma_f32 v[106:107], v[90:91], v[92:93], v[88:89]
	v_pk_mul_f32 v[148:149], v[106:107], v[106:107]
	s_waitcnt vmcnt(1)
	v_lshlrev_b32_e32 v140, 16, v168
	v_and_b32_e32 v141, 0xffff0000, v168
	s_waitcnt vmcnt(0)
	v_lshlrev_b32_e32 v150, 16, v172
	v_and_b32_e32 v151, 0xffff0000, v172
	v_pk_fma_f32 v[84:85], v[84:85], v[150:151], v[140:141]
	v_lshlrev_b32_e32 v140, 16, v170
	v_and_b32_e32 v141, 0xffff0000, v170
	v_lshlrev_b32_e32 v150, 16, v174
	v_and_b32_e32 v151, 0xffff0000, v174
	v_pk_fma_f32 v[140:141], v[80:81], v[150:151], v[140:141]
	v_mul_f32_e32 v81, 0xbfb8aa3b, v82
	v_exp_f32_e32 v81, v81
	v_mul_f32_e32 v80, 0xbfb8aa3b, v86
	v_exp_f32_e32 v80, v80
	v_lshlrev_b32_e32 v86, 16, v169
	v_add_f32_e32 v81, 1.0, v81
	v_rcp_f32_e32 v82, v81
	v_mul_f32_e32 v81, 0xbfb8aa3b, v87
	v_exp_f32_e32 v81, v81
	v_add_f32_e32 v80, 1.0, v80
	v_rcp_f32_e32 v80, v80
	v_and_b32_e32 v87, 0xffff0000, v169
	v_add_f32_e32 v81, 1.0, v81
	v_rcp_f32_e32 v81, v81
	v_lshlrev_b32_e32 v88, 16, v173
	v_and_b32_e32 v89, 0xffff0000, v173
	v_pk_fma_f32 v[92:93], v[80:81], v[88:89], v[86:87]
	v_mul_f32_e32 v80, 0xbfb8aa3b, v83
	v_exp_f32_e32 v80, v80
	v_and_b32_e32 v81, 0xffff0000, v171
	v_lshlrev_b32_e32 v86, 16, v175
	v_and_b32_e32 v87, 0xffff0000, v175
	v_add_f32_e32 v80, 1.0, v80
	v_rcp_f32_e32 v83, v80
	v_lshlrev_b32_e32 v80, 16, v171
	v_pk_mul_f32 v[88:89], v[140:141], v[140:141]
	v_pk_fma_f32 v[80:81], v[82:83], v[86:87], v[80:81]
	v_pk_mul_f32 v[82:83], v[84:85], v[84:85]
	v_pk_mul_f32 v[86:87], v[92:93], v[92:93]
	v_add_f32_e32 v82, v82, v83
	v_add_f32_e32 v86, v86, v87
	v_add_f32_e32 v82, v82, v86
	v_add_f32_e32 v86, v146, v147
	v_add_f32_e32 v87, v142, v143
	v_pk_mul_f32 v[90:91], v[80:81], v[80:81]
	v_add_f32_e32 v83, v88, v89
	v_add_f32_e32 v86, v87, v86
	v_add_f32_e32 v87, v144, v145
	v_add_f32_e32 v90, v90, v91
	v_add_f32_e32 v82, v83, v82
	v_add_f32_e32 v83, v148, v149
	v_add_f32_e32 v86, v87, v86
	v_add_f32_e32 v82, v90, v82
	v_add_f32_e32 v83, v83, v86
	v_add_f32_e32 v82, v83, v82
	ds_bpermute_b32 v83, v157, v82
	s_waitcnt lgkmcnt(0)
	v_add_f32_e32 v82, v82, v83
	ds_bpermute_b32 v83, v158, v82
	s_and_saveexec_b64 s[8:9], vcc
	s_cbranch_execz .LBB0_992
	s_waitcnt lgkmcnt(0)
	v_add_f32_e32 v82, v82, v83
	ds_write_b32 v159, v82 offset:512
.LBB0_992:
	s_or_b64 exec, exec, s[8:9]
	v_or_b32_e32 v82, 48, v138
	s_waitcnt lgkmcnt(0)
	v_ashrrev_i32_e32 v83, 31, v82
	v_lshlrev_b64 v[82:83], 10, v[82:83]
	v_lshl_add_u64 v[82:83], v[82:83], 0, v[128:129]
	v_lshlrev_b64 v[82:83], 1, v[82:83]
	v_lshl_add_u64 v[148:149], s[16:17], 0, v[82:83]
	v_lshl_add_u64 v[150:151], s[6:7], 0, v[82:83]
	global_load_dwordx4 v[88:91], v[148:149], off
	global_load_dwordx4 v[142:145], v[150:151], off
	global_load_dwordx4 v[168:171], v[148:149], off offset:256
	global_load_dwordx4 v[172:175], v[150:151], off offset:256
	v_mul_f32_e32 v76, 0xbfb8aa3b, v76
	v_mul_f32_e32 v77, 0xbfb8aa3b, v77
	v_exp_f32_e32 v76, v76
	v_mul_f32_e32 v72, 0xbfb8aa3b, v72
	v_exp_f32_e32 v77, v77
	v_mul_f32_e32 v73, 0xbfb8aa3b, v73
	v_exp_f32_e32 v72, v72
	v_exp_f32_e32 v73, v73
	v_add_f32_e32 v76, 1.0, v76
	v_add_f32_e32 v77, 1.0, v77
	v_rcp_f32_e32 v76, v76
	v_add_f32_e32 v72, 1.0, v72
	v_rcp_f32_e32 v77, v77
	v_add_f32_e32 v73, 1.0, v73
	v_rcp_f32_e32 v72, v72
	v_rcp_f32_e32 v73, v73
	v_mul_f32_e32 v68, 0xbfb8aa3b, v68
	v_mul_f32_e32 v69, 0xbfb8aa3b, v69
	v_mul_f32_e32 v70, 0xbfb8aa3b, v70
	v_mul_f32_e32 v71, 0xbfb8aa3b, v71
	v_exp_f32_e32 v68, v68
	v_exp_f32_e32 v69, v69
	v_exp_f32_e32 v70, v70
	v_mul_f32_e32 v66, 0xbfb8aa3b, v66
	v_exp_f32_e32 v71, v71
	v_mul_f32_e32 v67, 0xbfb8aa3b, v67
	v_mul_f32_e32 v64, 0xbfb8aa3b, v64
	v_mul_f32_e32 v65, 0xbfb8aa3b, v65
	v_exp_f32_e32 v66, v66
	v_exp_f32_e32 v67, v67
	v_exp_f32_e32 v64, v64
	v_exp_f32_e32 v65, v65
	v_add_f32_e32 v68, 1.0, v68
	v_add_f32_e32 v69, 1.0, v69
	v_add_f32_e32 v70, 1.0, v70
	v_add_f32_e32 v71, 1.0, v71
	v_rcp_f32_e32 v68, v68
	v_rcp_f32_e32 v69, v69
	v_rcp_f32_e32 v70, v70
	v_add_f32_e32 v66, 1.0, v66
	v_rcp_f32_e32 v71, v71
	v_add_f32_e32 v67, 1.0, v67
	v_add_f32_e32 v64, 1.0, v64
	v_add_f32_e32 v65, 1.0, v65
	v_rcp_f32_e32 v66, v66
	v_rcp_f32_e32 v67, v67
	v_rcp_f32_e32 v64, v64
	v_rcp_f32_e32 v65, v65
	s_waitcnt vmcnt(3)
	v_lshlrev_b32_e32 v82, 16, v88
	v_and_b32_e32 v83, 0xffff0000, v88
	s_waitcnt vmcnt(2)
	v_lshlrev_b32_e32 v86, 16, v142
	v_and_b32_e32 v87, 0xffff0000, v142
	v_pk_fma_f32 v[82:83], v[76:77], v[86:87], v[82:83]
	v_lshlrev_b32_e32 v76, 16, v90
	v_and_b32_e32 v77, 0xffff0000, v90
	v_lshlrev_b32_e32 v86, 16, v144
	v_and_b32_e32 v87, 0xffff0000, v144
	v_pk_fma_f32 v[86:87], v[72:73], v[86:87], v[76:77]
	v_mul_f32_e32 v73, 0xbfb8aa3b, v74
	v_exp_f32_e32 v73, v73
	v_mul_f32_e32 v72, 0xbfb8aa3b, v78
	v_exp_f32_e32 v72, v72
	v_lshlrev_b32_e32 v76, 16, v89
	v_add_f32_e32 v73, 1.0, v73
	v_rcp_f32_e32 v74, v73
	v_mul_f32_e32 v73, 0xbfb8aa3b, v79
	v_exp_f32_e32 v73, v73
	v_add_f32_e32 v72, 1.0, v72
	v_rcp_f32_e32 v72, v72
	v_and_b32_e32 v77, 0xffff0000, v89
	v_add_f32_e32 v73, 1.0, v73
	v_rcp_f32_e32 v73, v73
	v_lshlrev_b32_e32 v78, 16, v143
	v_and_b32_e32 v79, 0xffff0000, v143
	v_pk_mul_f32 v[94:95], v[82:83], v[82:83]
	v_pk_fma_f32 v[88:89], v[72:73], v[78:79], v[76:77]
	v_mul_f32_e32 v72, 0xbfb8aa3b, v75
	v_exp_f32_e32 v72, v72
	v_and_b32_e32 v73, 0xffff0000, v91
	v_lshlrev_b32_e32 v76, 16, v145
	v_and_b32_e32 v77, 0xffff0000, v145
	v_add_f32_e32 v72, 1.0, v72
	v_rcp_f32_e32 v75, v72
	v_lshlrev_b32_e32 v72, 16, v91
	v_pk_mul_f32 v[144:145], v[88:89], v[88:89]
	v_pk_mul_f32 v[142:143], v[86:87], v[86:87]
	v_pk_fma_f32 v[90:91], v[74:75], v[76:77], v[72:73]
	v_pk_mul_f32 v[146:147], v[90:91], v[90:91]
	s_waitcnt vmcnt(1)
	v_lshlrev_b32_e32 v148, 16, v168
	v_and_b32_e32 v149, 0xffff0000, v168
	s_waitcnt vmcnt(0)
	v_lshlrev_b32_e32 v150, 16, v172
	v_and_b32_e32 v151, 0xffff0000, v172
	v_lshlrev_b32_e32 v76, 16, v169
	v_and_b32_e32 v77, 0xffff0000, v169
	v_lshlrev_b32_e32 v72, 16, v173
	v_and_b32_e32 v73, 0xffff0000, v173
	v_pk_fma_f32 v[68:69], v[68:69], v[150:151], v[148:149]
	v_lshlrev_b32_e32 v150, 16, v174
	v_and_b32_e32 v151, 0xffff0000, v174
	v_pk_fma_f32 v[70:71], v[70:71], v[72:73], v[76:77]
	v_lshlrev_b32_e32 v72, 16, v171
	v_and_b32_e32 v73, 0xffff0000, v171
	v_lshlrev_b32_e32 v74, 16, v175
	v_and_b32_e32 v75, 0xffff0000, v175
	v_lshlrev_b32_e32 v148, 16, v170
	v_and_b32_e32 v149, 0xffff0000, v170
	v_pk_fma_f32 v[66:67], v[66:67], v[74:75], v[72:73]
	v_pk_mul_f32 v[72:73], v[68:69], v[68:69]
	v_pk_mul_f32 v[74:75], v[70:71], v[70:71]
	v_pk_fma_f32 v[64:65], v[64:65], v[150:151], v[148:149]
	v_add_f32_e32 v74, v74, v75
	v_add_f32_e32 v72, v72, v73
	v_pk_mul_f32 v[76:77], v[64:65], v[64:65]
	v_add_f32_e32 v72, v72, v74
	v_add_f32_e32 v74, v144, v145
	v_add_f32_e32 v75, v94, v95
	v_pk_mul_f32 v[78:79], v[66:67], v[66:67]
	v_add_f32_e32 v73, v76, v77
	v_add_f32_e32 v74, v75, v74
	v_add_f32_e32 v75, v142, v143
	v_add_f32_e32 v78, v78, v79
	v_add_f32_e32 v72, v73, v72
	v_add_f32_e32 v73, v146, v147
	v_add_f32_e32 v74, v75, v74
	v_add_f32_e32 v72, v78, v72
	v_add_f32_e32 v73, v73, v74
	v_add_f32_e32 v72, v73, v72
	ds_bpermute_b32 v73, v157, v72
	s_waitcnt lgkmcnt(0)
	v_add_f32_e32 v72, v72, v73
	ds_bpermute_b32 v73, v158, v72
	s_and_saveexec_b64 s[8:9], vcc
	s_cbranch_execz .LBB0_994
	s_waitcnt lgkmcnt(0)
	v_add_f32_e32 v72, v72, v73
	ds_write_b32 v159, v72 offset:768
.LBB0_994:
	s_or_b64 exec, exec, s[8:9]
	s_waitcnt lgkmcnt(0)
	v_lshlrev_b64 v[72:73], 10, v[138:139]
	v_lshl_add_u64 v[94:95], v[72:73], 0, v[128:129]
	v_mov_b64_e32 v[72:73], 0x40000
	v_lshl_add_u64 v[72:73], v[94:95], 1, v[72:73]
	v_lshl_add_u64 v[150:151], s[16:17], 0, v[72:73]
	v_lshl_add_u64 v[152:153], s[6:7], 0, v[72:73]
	global_load_dwordx4 v[76:79], v[150:151], off
	global_load_dwordx4 v[142:145], v[152:153], off
	global_load_dwordx4 v[168:171], v[150:151], off offset:256
	global_load_dwordx4 v[172:175], v[152:153], off offset:256
	v_mul_f32_e32 v60, 0xbfb8aa3b, v60
	v_mul_f32_e32 v61, 0xbfb8aa3b, v61
	v_exp_f32_e32 v60, v60
	v_mul_f32_e32 v56, 0xbfb8aa3b, v56
	v_exp_f32_e32 v61, v61
	v_mul_f32_e32 v57, 0xbfb8aa3b, v57
	v_exp_f32_e32 v56, v56
	v_exp_f32_e32 v57, v57
	v_add_f32_e32 v60, 1.0, v60
	v_add_f32_e32 v61, 1.0, v61
	v_rcp_f32_e32 v60, v60
	v_add_f32_e32 v56, 1.0, v56
	v_rcp_f32_e32 v61, v61
	v_add_f32_e32 v57, 1.0, v57
	v_rcp_f32_e32 v56, v56
	v_rcp_f32_e32 v57, v57
	v_mul_f32_e32 v52, 0xbfb8aa3b, v52
	v_mul_f32_e32 v53, 0xbfb8aa3b, v53
	v_mul_f32_e32 v54, 0xbfb8aa3b, v54
	v_mul_f32_e32 v55, 0xbfb8aa3b, v55
	v_exp_f32_e32 v52, v52
	v_mul_f32_e32 v48, 0xbfb8aa3b, v48
	v_exp_f32_e32 v53, v53
	v_mul_f32_e32 v49, 0xbfb8aa3b, v49
	v_exp_f32_e32 v54, v54
	v_mul_f32_e32 v50, 0xbfb8aa3b, v50
	v_exp_f32_e32 v55, v55
	v_mul_f32_e32 v51, 0xbfb8aa3b, v51
	v_exp_f32_e32 v48, v48
	v_exp_f32_e32 v49, v49
	v_exp_f32_e32 v50, v50
	v_exp_f32_e32 v51, v51
	v_add_f32_e32 v52, 1.0, v52
	v_add_f32_e32 v53, 1.0, v53
	v_add_f32_e32 v54, 1.0, v54
	v_add_f32_e32 v55, 1.0, v55
	v_rcp_f32_e32 v52, v52
	v_add_f32_e32 v48, 1.0, v48
	v_rcp_f32_e32 v53, v53
	v_add_f32_e32 v49, 1.0, v49
	v_rcp_f32_e32 v54, v54
	v_add_f32_e32 v50, 1.0, v50
	v_rcp_f32_e32 v55, v55
	v_add_f32_e32 v51, 1.0, v51
	v_rcp_f32_e32 v48, v48
	v_rcp_f32_e32 v49, v49
	v_rcp_f32_e32 v50, v50
	v_rcp_f32_e32 v51, v51
	v_add_u32_e32 v164, 0x80, v154
	s_waitcnt vmcnt(3)
	v_lshlrev_b32_e32 v72, 16, v76
	v_and_b32_e32 v73, 0xffff0000, v76
	s_waitcnt vmcnt(2)
	v_lshlrev_b32_e32 v74, 16, v142
	v_and_b32_e32 v75, 0xffff0000, v142
	v_pk_fma_f32 v[72:73], v[60:61], v[74:75], v[72:73]
	v_lshlrev_b32_e32 v60, 16, v78
	v_and_b32_e32 v61, 0xffff0000, v78
	v_lshlrev_b32_e32 v74, 16, v144
	v_and_b32_e32 v75, 0xffff0000, v144
	v_pk_fma_f32 v[74:75], v[56:57], v[74:75], v[60:61]
	v_mul_f32_e32 v57, 0xbfb8aa3b, v58
	v_exp_f32_e32 v57, v57
	v_mul_f32_e32 v56, 0xbfb8aa3b, v62
	v_exp_f32_e32 v56, v56
	v_lshlrev_b32_e32 v60, 16, v77
	v_add_f32_e32 v57, 1.0, v57
	v_rcp_f32_e32 v58, v57
	v_mul_f32_e32 v57, 0xbfb8aa3b, v63
	v_exp_f32_e32 v57, v57
	v_add_f32_e32 v56, 1.0, v56
	v_rcp_f32_e32 v56, v56
	v_and_b32_e32 v61, 0xffff0000, v77
	v_add_f32_e32 v57, 1.0, v57
	v_rcp_f32_e32 v57, v57
	v_lshlrev_b32_e32 v62, 16, v143
	v_and_b32_e32 v63, 0xffff0000, v143
	v_pk_mul_f32 v[146:147], v[74:75], v[74:75]
	v_pk_fma_f32 v[76:77], v[56:57], v[62:63], v[60:61]
	v_mul_f32_e32 v56, 0xbfb8aa3b, v59
	v_exp_f32_e32 v56, v56
	v_and_b32_e32 v57, 0xffff0000, v79
	v_lshlrev_b32_e32 v60, 16, v145
	v_and_b32_e32 v61, 0xffff0000, v145
	v_add_f32_e32 v56, 1.0, v56
	v_rcp_f32_e32 v59, v56
	v_lshlrev_b32_e32 v56, 16, v79
	v_pk_mul_f32 v[144:145], v[72:73], v[72:73]
	v_pk_mul_f32 v[148:149], v[76:77], v[76:77]
	v_pk_fma_f32 v[78:79], v[58:59], v[60:61], v[56:57]
	v_pk_mul_f32 v[142:143], v[78:79], v[78:79]
	s_waitcnt vmcnt(1)
	v_lshlrev_b32_e32 v150, 16, v168
	v_and_b32_e32 v151, 0xffff0000, v168
	s_waitcnt vmcnt(0)
	v_lshlrev_b32_e32 v152, 16, v172
	v_and_b32_e32 v153, 0xffff0000, v172
	v_lshlrev_b32_e32 v60, 16, v169
	v_and_b32_e32 v61, 0xffff0000, v169
	v_lshlrev_b32_e32 v56, 16, v173
	v_and_b32_e32 v57, 0xffff0000, v173
	v_pk_fma_f32 v[52:53], v[52:53], v[152:153], v[150:151]
	v_lshlrev_b32_e32 v150, 16, v170
	v_and_b32_e32 v151, 0xffff0000, v170
	v_lshlrev_b32_e32 v152, 16, v174
	v_and_b32_e32 v153, 0xffff0000, v174
	v_pk_fma_f32 v[54:55], v[54:55], v[56:57], v[60:61]
	v_lshlrev_b32_e32 v56, 16, v171
	v_and_b32_e32 v57, 0xffff0000, v171
	v_lshlrev_b32_e32 v58, 16, v175
	v_and_b32_e32 v59, 0xffff0000, v175
	v_pk_fma_f32 v[48:49], v[48:49], v[152:153], v[150:151]
	v_pk_fma_f32 v[50:51], v[50:51], v[58:59], v[56:57]
	v_pk_mul_f32 v[56:57], v[52:53], v[52:53]
	v_pk_mul_f32 v[58:59], v[54:55], v[54:55]
	v_pk_mul_f32 v[60:61], v[48:49], v[48:49]
	v_add_f32_e32 v58, v58, v59
	v_add_f32_e32 v56, v56, v57
	v_pk_mul_f32 v[62:63], v[50:51], v[50:51]
	v_add_f32_e32 v56, v56, v58
	v_add_f32_e32 v57, v60, v61
	v_add_f32_e32 v56, v57, v56
	v_add_f32_e32 v57, v62, v63
	v_add_f32_e32 v56, v57, v56
	v_add_f32_e32 v57, v148, v149
	v_add_f32_e32 v58, v144, v145
	v_add_f32_e32 v57, v58, v57
	v_add_f32_e32 v58, v146, v147
	v_add_f32_e32 v57, v58, v57
	v_add_f32_e32 v58, v142, v143
	v_add_f32_e32 v57, v58, v57
	v_add_f32_e32 v56, v57, v56
	ds_bpermute_b32 v57, v157, v56
	s_waitcnt lgkmcnt(0)
	v_add_f32_e32 v56, v56, v57
	ds_bpermute_b32 v57, v158, v56
	s_and_saveexec_b64 s[8:9], vcc
	s_cbranch_execz .LBB0_996
	v_lshl_add_u32 v58, v164, 4, s0
	s_waitcnt lgkmcnt(0)
	v_add_f32_e32 v56, v56, v57
	ds_write_b32 v58, v56
.LBB0_996:
	s_or_b64 exec, exec, s[8:9]
	s_waitcnt lgkmcnt(0)
	v_mov_b64_e32 v[56:57], 0x48000
	v_lshl_add_u64 v[56:57], v[94:95], 1, v[56:57]
	v_lshl_add_u64 v[148:149], s[16:17], 0, v[56:57]
	v_lshl_add_u64 v[150:151], s[6:7], 0, v[56:57]
	global_load_dwordx4 v[60:63], v[148:149], off
	global_load_dwordx4 v[142:145], v[150:151], off
	global_load_dwordx4 v[168:171], v[148:149], off offset:256
	global_load_dwordx4 v[172:175], v[150:151], off offset:256
	v_mul_f32_e32 v44, 0xbfb8aa3b, v44
	v_mul_f32_e32 v45, 0xbfb8aa3b, v45
	v_exp_f32_e32 v44, v44
	v_mul_f32_e32 v40, 0xbfb8aa3b, v40
	v_exp_f32_e32 v45, v45
	v_mul_f32_e32 v41, 0xbfb8aa3b, v41
	v_exp_f32_e32 v40, v40
	v_exp_f32_e32 v41, v41
	v_add_f32_e32 v44, 1.0, v44
	v_add_f32_e32 v45, 1.0, v45
	v_rcp_f32_e32 v44, v44
	v_add_f32_e32 v40, 1.0, v40
	v_rcp_f32_e32 v45, v45
	v_add_f32_e32 v41, 1.0, v41
	v_rcp_f32_e32 v40, v40
	v_rcp_f32_e32 v41, v41
	v_mul_f32_e32 v36, 0xbfb8aa3b, v36
	v_mul_f32_e32 v37, 0xbfb8aa3b, v37
	v_mul_f32_e32 v38, 0xbfb8aa3b, v38
	v_mul_f32_e32 v39, 0xbfb8aa3b, v39
	v_exp_f32_e32 v36, v36
	v_mul_f32_e32 v32, 0xbfb8aa3b, v32
	v_exp_f32_e32 v37, v37
	v_mul_f32_e32 v33, 0xbfb8aa3b, v33
	v_exp_f32_e32 v38, v38
	v_mul_f32_e32 v34, 0xbfb8aa3b, v34
	v_exp_f32_e32 v39, v39
	v_mul_f32_e32 v35, 0xbfb8aa3b, v35
	v_exp_f32_e32 v32, v32
	v_exp_f32_e32 v33, v33
	v_exp_f32_e32 v34, v34
	v_exp_f32_e32 v35, v35
	v_add_f32_e32 v36, 1.0, v36
	v_add_f32_e32 v37, 1.0, v37
	v_add_f32_e32 v38, 1.0, v38
	v_add_f32_e32 v39, 1.0, v39
	v_rcp_f32_e32 v36, v36
	v_add_f32_e32 v32, 1.0, v32
	v_rcp_f32_e32 v37, v37
	v_add_f32_e32 v33, 1.0, v33
	v_rcp_f32_e32 v38, v38
	v_add_f32_e32 v34, 1.0, v34
	v_rcp_f32_e32 v39, v39
	v_add_f32_e32 v35, 1.0, v35
	v_rcp_f32_e32 v32, v32
	v_rcp_f32_e32 v33, v33
	v_rcp_f32_e32 v34, v34
	v_rcp_f32_e32 v35, v35
	s_waitcnt vmcnt(3)
	v_lshlrev_b32_e32 v56, 16, v60
	v_and_b32_e32 v57, 0xffff0000, v60
	s_waitcnt vmcnt(2)
	v_lshlrev_b32_e32 v58, 16, v142
	v_and_b32_e32 v59, 0xffff0000, v142
	v_pk_fma_f32 v[56:57], v[44:45], v[58:59], v[56:57]
	v_lshlrev_b32_e32 v44, 16, v62
	v_and_b32_e32 v45, 0xffff0000, v62
	v_lshlrev_b32_e32 v58, 16, v144
	v_and_b32_e32 v59, 0xffff0000, v144
	v_pk_fma_f32 v[58:59], v[40:41], v[58:59], v[44:45]
	v_mul_f32_e32 v41, 0xbfb8aa3b, v42
	v_exp_f32_e32 v41, v41
	v_mul_f32_e32 v40, 0xbfb8aa3b, v46
	v_exp_f32_e32 v40, v40
	v_lshlrev_b32_e32 v44, 16, v61
	v_add_f32_e32 v41, 1.0, v41
	v_rcp_f32_e32 v42, v41
	v_mul_f32_e32 v41, 0xbfb8aa3b, v47
	v_exp_f32_e32 v41, v41
	v_add_f32_e32 v40, 1.0, v40
	v_rcp_f32_e32 v40, v40
	v_and_b32_e32 v45, 0xffff0000, v61
	v_add_f32_e32 v41, 1.0, v41
	v_rcp_f32_e32 v41, v41
	v_lshlrev_b32_e32 v46, 16, v143
	v_and_b32_e32 v47, 0xffff0000, v143
	v_pk_mul_f32 v[142:143], v[56:57], v[56:57]
	v_pk_fma_f32 v[60:61], v[40:41], v[46:47], v[44:45]
	v_mul_f32_e32 v40, 0xbfb8aa3b, v43
	v_exp_f32_e32 v40, v40
	v_and_b32_e32 v41, 0xffff0000, v63
	v_lshlrev_b32_e32 v44, 16, v145
	v_and_b32_e32 v45, 0xffff0000, v145
	v_add_f32_e32 v40, 1.0, v40
	v_rcp_f32_e32 v43, v40
	v_lshlrev_b32_e32 v40, 16, v63
	v_pk_mul_f32 v[146:147], v[60:61], v[60:61]
	v_pk_mul_f32 v[144:145], v[58:59], v[58:59]
	v_pk_fma_f32 v[62:63], v[42:43], v[44:45], v[40:41]
	v_pk_mul_f32 v[94:95], v[62:63], v[62:63]
	s_waitcnt vmcnt(1)
	v_lshlrev_b32_e32 v148, 16, v168
	v_and_b32_e32 v149, 0xffff0000, v168
	s_waitcnt vmcnt(0)
	v_lshlrev_b32_e32 v150, 16, v172
	v_and_b32_e32 v151, 0xffff0000, v172
	v_lshlrev_b32_e32 v44, 16, v169
	v_and_b32_e32 v45, 0xffff0000, v169
	v_lshlrev_b32_e32 v40, 16, v173
	v_and_b32_e32 v41, 0xffff0000, v173
	v_pk_fma_f32 v[36:37], v[36:37], v[150:151], v[148:149]
	v_lshlrev_b32_e32 v148, 16, v170
	v_and_b32_e32 v149, 0xffff0000, v170
	v_lshlrev_b32_e32 v150, 16, v174
	v_and_b32_e32 v151, 0xffff0000, v174
	v_pk_fma_f32 v[38:39], v[38:39], v[40:41], v[44:45]
	v_lshlrev_b32_e32 v40, 16, v171
	v_and_b32_e32 v41, 0xffff0000, v171
	v_lshlrev_b32_e32 v42, 16, v175
	v_and_b32_e32 v43, 0xffff0000, v175
	v_pk_fma_f32 v[32:33], v[32:33], v[150:151], v[148:149]
	v_pk_fma_f32 v[34:35], v[34:35], v[42:43], v[40:41]
	v_pk_mul_f32 v[40:41], v[36:37], v[36:37]
	v_pk_mul_f32 v[42:43], v[38:39], v[38:39]
	v_pk_mul_f32 v[44:45], v[32:33], v[32:33]
	v_add_f32_e32 v42, v42, v43
	v_add_f32_e32 v40, v40, v41
	v_pk_mul_f32 v[46:47], v[34:35], v[34:35]
	v_add_f32_e32 v40, v40, v42
	v_add_f32_e32 v41, v44, v45
	v_add_f32_e32 v40, v41, v40
	v_add_f32_e32 v41, v46, v47
	v_add_f32_e32 v40, v41, v40
	v_add_f32_e32 v41, v146, v147
	v_add_f32_e32 v42, v142, v143
	v_add_f32_e32 v41, v42, v41
	v_add_f32_e32 v42, v144, v145
	v_add_f32_e32 v41, v42, v41
	v_add_f32_e32 v42, v94, v95
	v_add_f32_e32 v41, v42, v41
	v_add_f32_e32 v40, v41, v40
	ds_bpermute_b32 v41, v157, v40
	s_waitcnt lgkmcnt(0)
	v_add_f32_e32 v40, v40, v41
	ds_bpermute_b32 v41, v158, v40
	s_and_saveexec_b64 s[8:9], vcc
	s_cbranch_execz .LBB0_998
	s_waitcnt lgkmcnt(0)
	v_add_f32_e32 v40, v40, v41
	ds_write_b32 v159, v40 offset:2304
.LBB0_998:
	s_or_b64 exec, exec, s[8:9]
	s_waitcnt lgkmcnt(0)
	v_lshlrev_b64 v[40:41], 10, v[138:139]
	v_lshl_add_u64 v[94:95], v[40:41], 0, v[128:129]
	v_mov_b64_e32 v[40:41], 0x50000
	v_lshl_add_u64 v[40:41], v[94:95], 1, v[40:41]
	v_lshl_add_u64 v[148:149], s[16:17], 0, v[40:41]
	v_lshl_add_u64 v[150:151], s[6:7], 0, v[40:41]
	global_load_dwordx4 v[44:47], v[148:149], off
	global_load_dwordx4 v[142:145], v[150:151], off
	global_load_dwordx4 v[168:171], v[148:149], off offset:256
	global_load_dwordx4 v[172:175], v[150:151], off offset:256
	v_mul_f32_e32 v28, 0xbfb8aa3b, v28
	v_mul_f32_e32 v29, 0xbfb8aa3b, v29
	v_exp_f32_e32 v28, v28
	v_mul_f32_e32 v24, 0xbfb8aa3b, v24
	v_exp_f32_e32 v29, v29
	v_mul_f32_e32 v25, 0xbfb8aa3b, v25
	v_exp_f32_e32 v24, v24
	v_exp_f32_e32 v25, v25
	v_add_f32_e32 v28, 1.0, v28
	v_add_f32_e32 v29, 1.0, v29
	v_rcp_f32_e32 v28, v28
	v_add_f32_e32 v24, 1.0, v24
	v_rcp_f32_e32 v29, v29
	v_add_f32_e32 v25, 1.0, v25
	v_rcp_f32_e32 v24, v24
	v_rcp_f32_e32 v25, v25
	v_mul_f32_e32 v20, 0xbfb8aa3b, v20
	v_mul_f32_e32 v21, 0xbfb8aa3b, v21
	v_mul_f32_e32 v22, 0xbfb8aa3b, v22
	v_mul_f32_e32 v23, 0xbfb8aa3b, v23
	v_exp_f32_e32 v20, v20
	v_mul_f32_e32 v16, 0xbfb8aa3b, v16
	v_exp_f32_e32 v21, v21
	v_mul_f32_e32 v17, 0xbfb8aa3b, v17
	v_exp_f32_e32 v22, v22
	v_mul_f32_e32 v18, 0xbfb8aa3b, v18
	v_exp_f32_e32 v23, v23
	v_mul_f32_e32 v19, 0xbfb8aa3b, v19
	v_exp_f32_e32 v16, v16
	v_exp_f32_e32 v17, v17
	v_exp_f32_e32 v18, v18
	v_exp_f32_e32 v19, v19
	v_add_f32_e32 v20, 1.0, v20
	v_add_f32_e32 v21, 1.0, v21
	v_add_f32_e32 v22, 1.0, v22
	v_add_f32_e32 v23, 1.0, v23
	v_rcp_f32_e32 v20, v20
	v_add_f32_e32 v16, 1.0, v16
	v_rcp_f32_e32 v21, v21
	v_add_f32_e32 v17, 1.0, v17
	v_rcp_f32_e32 v22, v22
	v_add_f32_e32 v18, 1.0, v18
	v_rcp_f32_e32 v23, v23
	v_add_f32_e32 v19, 1.0, v19
	v_rcp_f32_e32 v16, v16
	v_rcp_f32_e32 v17, v17
	v_rcp_f32_e32 v18, v18
	v_rcp_f32_e32 v19, v19
	s_waitcnt vmcnt(3)
	v_lshlrev_b32_e32 v40, 16, v44
	v_and_b32_e32 v41, 0xffff0000, v44
	s_waitcnt vmcnt(2)
	v_lshlrev_b32_e32 v42, 16, v142
	v_and_b32_e32 v43, 0xffff0000, v142
	v_pk_fma_f32 v[40:41], v[28:29], v[42:43], v[40:41]
	v_lshlrev_b32_e32 v28, 16, v46
	v_and_b32_e32 v29, 0xffff0000, v46
	v_lshlrev_b32_e32 v42, 16, v144
	v_and_b32_e32 v43, 0xffff0000, v144
	v_pk_fma_f32 v[42:43], v[24:25], v[42:43], v[28:29]
	v_mul_f32_e32 v25, 0xbfb8aa3b, v26
	v_exp_f32_e32 v25, v25
	v_mul_f32_e32 v24, 0xbfb8aa3b, v30
	v_exp_f32_e32 v24, v24
	v_lshlrev_b32_e32 v28, 16, v45
	v_add_f32_e32 v25, 1.0, v25
	v_rcp_f32_e32 v26, v25
	v_mul_f32_e32 v25, 0xbfb8aa3b, v31
	v_exp_f32_e32 v25, v25
	v_add_f32_e32 v24, 1.0, v24
	v_rcp_f32_e32 v24, v24
	v_and_b32_e32 v29, 0xffff0000, v45
	v_add_f32_e32 v25, 1.0, v25
	v_rcp_f32_e32 v25, v25
	v_lshlrev_b32_e32 v30, 16, v143
	v_and_b32_e32 v31, 0xffff0000, v143
	v_pk_mul_f32 v[142:143], v[40:41], v[40:41]
	v_pk_fma_f32 v[44:45], v[24:25], v[30:31], v[28:29]
	v_mul_f32_e32 v24, 0xbfb8aa3b, v27
	v_exp_f32_e32 v24, v24
	v_and_b32_e32 v25, 0xffff0000, v47
	v_lshlrev_b32_e32 v28, 16, v145
	v_and_b32_e32 v29, 0xffff0000, v145
	v_add_f32_e32 v24, 1.0, v24
	v_rcp_f32_e32 v27, v24
	v_lshlrev_b32_e32 v24, 16, v47
	v_pk_mul_f32 v[146:147], v[44:45], v[44:45]
	v_pk_mul_f32 v[144:145], v[42:43], v[42:43]
	v_pk_fma_f32 v[46:47], v[26:27], v[28:29], v[24:25]
	v_pk_mul_f32 v[138:139], v[46:47], v[46:47]
	s_waitcnt vmcnt(1)
	v_lshlrev_b32_e32 v148, 16, v168
	v_and_b32_e32 v149, 0xffff0000, v168
	s_waitcnt vmcnt(0)
	v_lshlrev_b32_e32 v150, 16, v172
	v_and_b32_e32 v151, 0xffff0000, v172
	v_lshlrev_b32_e32 v28, 16, v169
	v_and_b32_e32 v29, 0xffff0000, v169
	v_lshlrev_b32_e32 v24, 16, v173
	v_and_b32_e32 v25, 0xffff0000, v173
	v_pk_fma_f32 v[20:21], v[20:21], v[150:151], v[148:149]
	v_lshlrev_b32_e32 v148, 16, v170
	v_and_b32_e32 v149, 0xffff0000, v170
	v_lshlrev_b32_e32 v150, 16, v174
	v_and_b32_e32 v151, 0xffff0000, v174
	v_pk_fma_f32 v[22:23], v[22:23], v[24:25], v[28:29]
	v_lshlrev_b32_e32 v24, 16, v171
	v_and_b32_e32 v25, 0xffff0000, v171
	v_lshlrev_b32_e32 v26, 16, v175
	v_and_b32_e32 v27, 0xffff0000, v175
	v_pk_fma_f32 v[16:17], v[16:17], v[150:151], v[148:149]
	v_pk_fma_f32 v[18:19], v[18:19], v[26:27], v[24:25]
	v_pk_mul_f32 v[24:25], v[20:21], v[20:21]
	v_pk_mul_f32 v[26:27], v[22:23], v[22:23]
	v_pk_mul_f32 v[28:29], v[16:17], v[16:17]
	v_add_f32_e32 v26, v26, v27
	v_add_f32_e32 v24, v24, v25
	v_pk_mul_f32 v[30:31], v[18:19], v[18:19]
	v_add_f32_e32 v24, v24, v26
	v_add_f32_e32 v25, v28, v29
	v_add_f32_e32 v24, v25, v24
	v_add_f32_e32 v25, v30, v31
	v_add_f32_e32 v24, v25, v24
	v_add_f32_e32 v25, v146, v147
	v_add_f32_e32 v26, v142, v143
	v_add_f32_e32 v25, v26, v25
	v_add_f32_e32 v26, v144, v145
	v_add_f32_e32 v25, v26, v25
	v_add_f32_e32 v26, v138, v139
	v_add_f32_e32 v25, v26, v25
	v_add_f32_e32 v24, v25, v24
	ds_bpermute_b32 v25, v157, v24
	s_waitcnt lgkmcnt(0)
	v_add_f32_e32 v24, v24, v25
	ds_bpermute_b32 v25, v158, v24
	s_and_saveexec_b64 s[8:9], vcc
	s_cbranch_execz .LBB0_1000
	s_waitcnt lgkmcnt(0)
	v_add_f32_e32 v24, v24, v25
	ds_write_b32 v159, v24 offset:2560
.LBB0_1000:
	s_or_b64 exec, exec, s[8:9]
	s_waitcnt lgkmcnt(0)
	v_lshl_add_u64 v[24:25], v[94:95], 1, v[208:209]
	v_lshl_add_u64 v[94:95], s[16:17], 0, v[24:25]
	v_lshl_add_u64 v[138:139], s[6:7], 0, v[24:25]
	global_load_dwordx4 v[28:31], v[94:95], off
	global_load_dwordx4 v[142:145], v[138:139], off
	global_load_dwordx4 v[168:171], v[94:95], off offset:256
	global_load_dwordx4 v[172:175], v[138:139], off offset:256
	v_mul_f32_e32 v12, 0xbfb8aa3b, v12
	v_mul_f32_e32 v13, 0xbfb8aa3b, v13
	v_exp_f32_e32 v12, v12
	v_mul_f32_e32 v8, 0xbfb8aa3b, v8
	v_exp_f32_e32 v13, v13
	v_mul_f32_e32 v9, 0xbfb8aa3b, v9
	v_exp_f32_e32 v8, v8
	v_exp_f32_e32 v9, v9
	v_add_f32_e32 v12, 1.0, v12
	v_add_f32_e32 v13, 1.0, v13
	v_rcp_f32_e32 v12, v12
	v_add_f32_e32 v8, 1.0, v8
	v_rcp_f32_e32 v13, v13
	v_add_f32_e32 v9, 1.0, v9
	v_rcp_f32_e32 v8, v8
	v_rcp_f32_e32 v9, v9
	v_mul_f32_e32 v4, 0xbfb8aa3b, v4
	v_mul_f32_e32 v5, 0xbfb8aa3b, v5
	v_exp_f32_e32 v4, v4
	v_mul_f32_e32 v0, 0xbfb8aa3b, v0
	v_exp_f32_e32 v5, v5
	v_mul_f32_e32 v1, 0xbfb8aa3b, v1
	v_exp_f32_e32 v0, v0
	v_exp_f32_e32 v1, v1
	v_add_f32_e32 v4, 1.0, v4
	v_add_f32_e32 v5, 1.0, v5
	v_rcp_f32_e32 v4, v4
	v_add_f32_e32 v0, 1.0, v0
	v_rcp_f32_e32 v5, v5
	v_add_f32_e32 v1, 1.0, v1
	v_rcp_f32_e32 v0, v0
	v_rcp_f32_e32 v1, v1
	s_waitcnt vmcnt(3)
	v_lshlrev_b32_e32 v24, 16, v28
	v_and_b32_e32 v25, 0xffff0000, v28
	s_waitcnt vmcnt(2)
	v_lshlrev_b32_e32 v26, 16, v142
	v_and_b32_e32 v27, 0xffff0000, v142
	v_pk_fma_f32 v[24:25], v[12:13], v[26:27], v[24:25]
	v_lshlrev_b32_e32 v12, 16, v30
	v_and_b32_e32 v13, 0xffff0000, v30
	v_lshlrev_b32_e32 v26, 16, v144
	v_and_b32_e32 v27, 0xffff0000, v144
	v_pk_fma_f32 v[26:27], v[8:9], v[26:27], v[12:13]
	v_mul_f32_e32 v9, 0xbfb8aa3b, v10
	v_exp_f32_e32 v9, v9
	v_mul_f32_e32 v8, 0xbfb8aa3b, v14
	v_exp_f32_e32 v8, v8
	v_lshlrev_b32_e32 v12, 16, v29
	v_add_f32_e32 v9, 1.0, v9
	v_rcp_f32_e32 v10, v9
	v_mul_f32_e32 v9, 0xbfb8aa3b, v15
	v_exp_f32_e32 v9, v9
	v_add_f32_e32 v8, 1.0, v8
	v_rcp_f32_e32 v8, v8
	v_and_b32_e32 v13, 0xffff0000, v29
	v_add_f32_e32 v9, 1.0, v9
	v_rcp_f32_e32 v9, v9
	v_lshlrev_b32_e32 v14, 16, v143
	v_and_b32_e32 v15, 0xffff0000, v143
	v_pk_mul_f32 v[148:149], v[24:25], v[24:25]
	v_pk_fma_f32 v[28:29], v[8:9], v[14:15], v[12:13]
	v_mul_f32_e32 v8, 0xbfb8aa3b, v11
	v_exp_f32_e32 v8, v8
	v_and_b32_e32 v9, 0xffff0000, v31
	v_lshlrev_b32_e32 v12, 16, v145
	v_and_b32_e32 v13, 0xffff0000, v145
	v_add_f32_e32 v8, 1.0, v8
	v_rcp_f32_e32 v11, v8
	v_lshlrev_b32_e32 v8, 16, v31
	v_pk_mul_f32 v[152:153], v[28:29], v[28:29]
	v_pk_mul_f32 v[150:151], v[26:27], v[26:27]
	v_pk_fma_f32 v[30:31], v[10:11], v[12:13], v[8:9]
	v_pk_mul_f32 v[146:147], v[30:31], v[30:31]
	s_waitcnt vmcnt(1)
	v_lshlrev_b32_e32 v94, 16, v168
	v_and_b32_e32 v95, 0xffff0000, v168
	s_waitcnt vmcnt(0)
	v_lshlrev_b32_e32 v138, 16, v172
	v_and_b32_e32 v139, 0xffff0000, v172
	v_pk_fma_f32 v[94:95], v[4:5], v[138:139], v[94:95]
	v_lshlrev_b32_e32 v4, 16, v170
	v_and_b32_e32 v5, 0xffff0000, v170
	v_lshlrev_b32_e32 v138, 16, v174
	v_and_b32_e32 v139, 0xffff0000, v174
	v_pk_fma_f32 v[138:139], v[0:1], v[138:139], v[4:5]
	v_mul_f32_e32 v1, 0xbfb8aa3b, v2
	v_exp_f32_e32 v1, v1
	v_mul_f32_e32 v0, 0xbfb8aa3b, v6
	v_exp_f32_e32 v0, v0
	v_lshlrev_b32_e32 v4, 16, v169
	v_add_f32_e32 v1, 1.0, v1
	v_rcp_f32_e32 v2, v1
	v_mul_f32_e32 v1, 0xbfb8aa3b, v7
	v_exp_f32_e32 v1, v1
	v_add_f32_e32 v0, 1.0, v0
	v_rcp_f32_e32 v0, v0
	v_and_b32_e32 v5, 0xffff0000, v169
	v_add_f32_e32 v1, 1.0, v1
	v_rcp_f32_e32 v1, v1
	v_lshlrev_b32_e32 v6, 16, v173
	v_and_b32_e32 v7, 0xffff0000, v173
	v_pk_fma_f32 v[142:143], v[0:1], v[6:7], v[4:5]
	v_mul_f32_e32 v0, 0xbfb8aa3b, v3
	v_exp_f32_e32 v0, v0
	v_and_b32_e32 v1, 0xffff0000, v171
	v_lshlrev_b32_e32 v4, 16, v175
	v_and_b32_e32 v5, 0xffff0000, v175
	v_add_f32_e32 v0, 1.0, v0
	v_rcp_f32_e32 v3, v0
	v_lshlrev_b32_e32 v0, 16, v171
	v_pk_fma_f32 v[144:145], v[2:3], v[4:5], v[0:1]
	v_pk_mul_f32 v[0:1], v[94:95], v[94:95]
	v_pk_mul_f32 v[2:3], v[142:143], v[142:143]
	v_pk_mul_f32 v[4:5], v[138:139], v[138:139]
	v_add_f32_e32 v2, v2, v3
	v_add_f32_e32 v0, v0, v1
	v_pk_mul_f32 v[6:7], v[144:145], v[144:145]
	v_add_f32_e32 v0, v0, v2
	v_add_f32_e32 v1, v4, v5
	v_add_f32_e32 v0, v1, v0
	v_add_f32_e32 v1, v6, v7
	v_add_f32_e32 v0, v1, v0
	v_add_f32_e32 v1, v152, v153
	v_add_f32_e32 v2, v148, v149
	v_add_f32_e32 v1, v2, v1
	v_add_f32_e32 v2, v150, v151
	v_add_f32_e32 v1, v2, v1
	v_add_f32_e32 v2, v146, v147
	v_add_f32_e32 v1, v2, v1
	v_add_f32_e32 v0, v1, v0
	ds_bpermute_b32 v1, v157, v0
	s_waitcnt lgkmcnt(0)
	v_add_f32_e32 v0, v0, v1
	ds_bpermute_b32 v1, v158, v0
	s_and_saveexec_b64 s[6:7], vcc
	s_cbranch_execz .LBB0_1002
	s_waitcnt lgkmcnt(0)
	v_add_f32_e32 v0, v0, v1
	ds_write_b32 v159, v0 offset:2816

.LBB0_1041:
	s_add_u32 s12, s14, 0xdb00000
	s_addc_u32 s13, s15, 0
	s_lshl_b32 s2, s6, 8
	s_add_i32 s4, s2, s4
	s_lshl_b32 s7, s3, 5
	v_or_b32_e32 v128, s4, v143
	s_lshl_b32 s4, s8, 8
	v_lshrrev_b32_e32 v129, 1, v142
	s_or_b32 s4, s4, s7
	v_and_or_b32 v144, v129, 24, s4
	v_ashrrev_i32_e32 v129, 31, v128
	v_ashrrev_i32_e32 v145, 31, v144
	v_lshlrev_b64 v[130:131], 10, v[128:129]
	v_lshl_add_u64 v[138:139], v[130:131], 0, v[144:145]
	v_lshlrev_b64 v[134:135], 1, v[138:139]
	v_lshl_add_u64 v[140:141], s[16:17], 0, v[134:135]
	v_lshl_add_u64 v[148:149], s[12:13], 0, v[134:135]
	s_barrier
	global_load_dwordx4 v[130:133], v[140:141], off
	global_load_dwordx4 v[134:137], v[148:149], off
	global_load_dwordx4 v[168:171], v[140:141], off offset:256
	global_load_dwordx4 v[172:175], v[148:149], off offset:256
	v_mul_f32_e32 v76, 0xbfb8aa3b, v76
	v_mul_f32_e32 v77, 0xbfb8aa3b, v77
	v_mul_f32_e32 v78, 0xbfb8aa3b, v78
	v_mul_f32_e32 v79, 0xbfb8aa3b, v79
	v_mul_f32_e32 v72, 0xbfb8aa3b, v72
	v_mul_f32_e32 v73, 0xbfb8aa3b, v73
	v_mul_f32_e32 v74, 0xbfb8aa3b, v74
	v_mul_f32_e32 v75, 0xbfb8aa3b, v75
	v_exp_f32_e32 v76, v76
	v_exp_f32_e32 v77, v77
	v_exp_f32_e32 v78, v78
	v_exp_f32_e32 v79, v79
	v_exp_f32_e32 v72, v72
	v_exp_f32_e32 v73, v73
	v_exp_f32_e32 v74, v74
	v_exp_f32_e32 v75, v75
	v_add_f32_e32 v76, 1.0, v76
	v_add_f32_e32 v77, 1.0, v77
	v_add_f32_e32 v78, 1.0, v78
	v_add_f32_e32 v79, 1.0, v79
	v_add_f32_e32 v143, 1.0, v72
	v_add_f32_e32 v147, 1.0, v73
	v_add_f32_e32 v150, 1.0, v74
	v_add_f32_e32 v151, 1.0, v75
	v_rcp_f32_e32 v72, v76
	v_rcp_f32_e32 v73, v77
	v_rcp_f32_e32 v78, v78
	v_rcp_f32_e32 v79, v79
	v_rcp_f32_e32 v74, v143
	v_rcp_f32_e32 v75, v147
	v_rcp_f32_e32 v150, v150
	v_rcp_f32_e32 v151, v151
	v_readlane_b32 s20, v254, 0
	v_readlane_b32 s26, v254, 6
	v_readlane_b32 s27, v254, 7
	v_mul_f32_e32 v96, 0xbfb8aa3b, v96
	v_mul_f32_e32 v92, 0xbfb8aa3b, v92
	v_lshl_add_u64 v[152:153], v[138:139], 2, s[26:27]
	v_mul_f32_e32 v97, 0xbfb8aa3b, v97
	v_mul_f32_e32 v93, 0xbfb8aa3b, v93
	v_mul_f32_e32 v94, 0xbfb8aa3b, v94
	v_mul_f32_e32 v95, 0xbfb8aa3b, v95
	v_mul_f32_e32 v98, 0xbfb8aa3b, v98
	v_mul_f32_e32 v99, 0xbfb8aa3b, v99
	v_exp_f32_e32 v96, v96
	v_exp_f32_e32 v92, v92
	v_exp_f32_e32 v97, v97
	v_exp_f32_e32 v93, v93
	v_exp_f32_e32 v94, v94
	v_exp_f32_e32 v95, v95
	v_exp_f32_e32 v98, v98
	v_exp_f32_e32 v99, v99
	v_add_f32_e32 v96, 1.0, v96
	v_add_f32_e32 v97, 1.0, v97
	v_add_f32_e32 v98, 1.0, v98
	v_add_f32_e32 v99, 1.0, v99
	v_rcp_f32_e32 v98, v98
	v_rcp_f32_e32 v99, v99
	v_xor_b32_e32 v143, 32, v227
	s_lshl_b32 s3, s3, 2
	s_add_i32 s3, s3, 0
	v_readlane_b32 s21, v254, 1
	v_readlane_b32 s22, v254, 2
	v_readlane_b32 s23, v254, 3
	v_readlane_b32 s24, v254, 4
	v_readlane_b32 s25, v254, 5
	s_waitcnt vmcnt(2)
	v_lshlrev_b32_e32 v76, 16, v130
	v_and_b32_e32 v77, 0xffff0000, v130
	v_lshlrev_b32_e32 v138, 16, v134
	v_and_b32_e32 v139, 0xffff0000, v134
	v_lshlrev_b32_e32 v130, 16, v131
	v_and_b32_e32 v131, 0xffff0000, v131
	v_lshlrev_b32_e32 v134, 16, v135
	v_and_b32_e32 v135, 0xffff0000, v135
	v_lshlrev_b32_e32 v154, 16, v132
	v_and_b32_e32 v155, 0xffff0000, v132
	v_lshlrev_b32_e32 v156, 16, v136
	v_and_b32_e32 v157, 0xffff0000, v136
	v_lshlrev_b32_e32 v132, 16, v133
	v_and_b32_e32 v133, 0xffff0000, v133
	v_lshlrev_b32_e32 v136, 16, v137
	v_and_b32_e32 v137, 0xffff0000, v137
	v_pk_fma_f32 v[76:77], v[72:73], v[138:139], v[76:77]
	v_pk_fma_f32 v[78:79], v[78:79], v[134:135], v[130:131]
	v_pk_fma_f32 v[72:73], v[74:75], v[156:157], v[154:155]
	v_pk_fma_f32 v[74:75], v[150:151], v[136:137], v[132:133]
	global_store_dwordx4 v[152:153], v[76:79], off nt
	global_store_dwordx4 v[152:153], v[72:75], off offset:16 nt
	s_nop 0
	v_and_b32_e32 v131, 64, v227
	v_xor_b32_e32 v130, 16, v227
	v_add_u32_e32 v147, 64, v131
	v_cmp_lt_i32_e32 vcc, v130, v147
	v_add_f32_e32 v131, 1.0, v93
	v_add_f32_e32 v148, 1.0, v94
	v_cndmask_b32_e32 v130, v227, v130, vcc
	v_lshlrev_b32_e32 v133, 2, v130
	v_add_f32_e32 v130, 1.0, v92
	v_add_f32_e32 v149, 1.0, v95
	v_rcp_f32_e32 v92, v96
	v_rcp_f32_e32 v94, v130
	v_rcp_f32_e32 v93, v97
	v_rcp_f32_e32 v95, v131
	v_rcp_f32_e32 v130, v148
	v_rcp_f32_e32 v131, v149
	v_pk_mul_f32 v[96:97], v[76:77], v[76:77]
	v_pk_mul_f32 v[148:149], v[78:79], v[78:79]
	v_pk_mul_f32 v[150:151], v[72:73], v[72:73]
	v_add_f32_e32 v148, v148, v149
	v_add_f32_e32 v96, v96, v97
	v_pk_mul_f32 v[154:155], v[74:75], v[74:75]
	v_add_f32_e32 v97, v150, v151
	v_add_f32_e32 v96, v96, v148
	v_add_f32_e32 v154, v154, v155
	v_add_f32_e32 v96, v97, v96
	v_add_f32_e32 v156, v154, v96
	v_cmp_lt_i32_e32 vcc, v143, v147
	v_and_b32_e32 v132, 63, v142
	s_waitcnt vmcnt(3)
	v_lshlrev_b32_e32 v96, 16, v168
	v_and_b32_e32 v97, 0xffff0000, v168
	s_waitcnt vmcnt(2)
	v_lshlrev_b32_e32 v148, 16, v172
	v_and_b32_e32 v149, 0xffff0000, v172
	v_lshlrev_b32_e32 v134, 16, v169
	v_and_b32_e32 v135, 0xffff0000, v169
	v_lshlrev_b32_e32 v138, 16, v173
	v_and_b32_e32 v139, 0xffff0000, v173
	v_lshlrev_b32_e32 v150, 16, v170
	v_and_b32_e32 v151, 0xffff0000, v170
	v_lshlrev_b32_e32 v154, 16, v174
	v_and_b32_e32 v155, 0xffff0000, v174
	v_lshlrev_b32_e32 v136, 16, v171
	v_and_b32_e32 v137, 0xffff0000, v171
	v_lshlrev_b32_e32 v140, 16, v175
	v_and_b32_e32 v141, 0xffff0000, v175
	v_pk_fma_f32 v[96:97], v[92:93], v[148:149], v[96:97]
	v_pk_fma_f32 v[98:99], v[98:99], v[138:139], v[134:135]
	v_pk_fma_f32 v[92:93], v[94:95], v[154:155], v[150:151]
	v_pk_fma_f32 v[94:95], v[130:131], v[140:141], v[136:137]
	v_pk_mul_f32 v[130:131], v[96:97], v[96:97]
	v_pk_mul_f32 v[134:135], v[98:99], v[98:99]
	v_pk_mul_f32 v[136:137], v[92:93], v[92:93]
	v_add_f32_e32 v134, v134, v135
	v_add_f32_e32 v130, v130, v131
	v_pk_mul_f32 v[138:139], v[94:95], v[94:95]
	v_add_f32_e32 v131, v136, v137
	v_add_f32_e32 v130, v130, v134
	v_add_f32_e32 v138, v138, v139
	v_add_f32_e32 v130, v131, v130
	v_add_f32_e32 v130, v138, v130
	v_add_f32_e32 v130, v156, v130
	ds_bpermute_b32 v131, v133, v130
	v_cndmask_b32_e32 v134, v227, v143, vcc
	v_lshlrev_b32_e32 v135, 2, v134
	v_cmp_gt_u32_e32 vcc, 16, v132
	v_lshl_add_u32 v134, v146, 4, s3
	s_waitcnt lgkmcnt(0)
	v_add_f32_e32 v130, v130, v131
	ds_bpermute_b32 v131, v135, v130
	global_store_dwordx4 v[152:153], v[96:99], off offset:512 nt
	global_store_dwordx4 v[152:153], v[92:95], off offset:528 nt
	s_and_saveexec_b64 s[18:19], vcc
	s_cbranch_execz .LBB0_1043
	s_waitcnt lgkmcnt(0)
	v_add_f32_e32 v130, v130, v131
	ds_write_b32 v134, v130
.LBB0_1043:
	s_or_b64 exec, exec, s[18:19]
	v_or_b32_e32 v130, 16, v128
	s_waitcnt lgkmcnt(0)
	v_ashrrev_i32_e32 v131, 31, v130
	v_lshlrev_b64 v[130:131], 10, v[130:131]
	v_lshl_add_u64 v[130:131], v[130:131], 0, v[144:145]
	v_lshlrev_b64 v[140:141], 1, v[130:131]
	v_lshl_add_u64 v[152:153], s[16:17], 0, v[140:141]
	v_lshl_add_u64 v[140:141], s[12:13], 0, v[140:141]
	global_load_dwordx4 v[136:139], v[152:153], off
	global_load_dwordx4 v[148:151], v[140:141], off
	global_load_dwordx4 v[168:171], v[152:153], off offset:256
	global_load_dwordx4 v[172:175], v[140:141], off offset:256
	v_mul_f32_e32 v116, 0xbfb8aa3b, v116
	v_mul_f32_e32 v117, 0xbfb8aa3b, v117
	v_mul_f32_e32 v118, 0xbfb8aa3b, v118
	v_mul_f32_e32 v119, 0xbfb8aa3b, v119
	v_mul_f32_e32 v112, 0xbfb8aa3b, v112
	v_mul_f32_e32 v113, 0xbfb8aa3b, v113
	v_mul_f32_e32 v114, 0xbfb8aa3b, v114
	v_mul_f32_e32 v115, 0xbfb8aa3b, v115
	v_exp_f32_e32 v116, v116
	v_exp_f32_e32 v117, v117
	v_exp_f32_e32 v118, v118
	v_exp_f32_e32 v119, v119
	v_exp_f32_e32 v112, v112
	v_exp_f32_e32 v113, v113
	v_exp_f32_e32 v114, v114
	v_exp_f32_e32 v115, v115
	v_readlane_b32 s20, v254, 0
	v_readlane_b32 s26, v254, 6
	v_readlane_b32 s27, v254, 7
	v_add_f32_e32 v116, 1.0, v116
	v_add_f32_e32 v117, 1.0, v117
	v_add_f32_e32 v118, 1.0, v118
	v_add_f32_e32 v119, 1.0, v119
	v_lshl_add_u64 v[154:155], v[130:131], 2, s[26:27]
	v_add_f32_e32 v130, 1.0, v112
	v_add_f32_e32 v131, 1.0, v113
	v_add_f32_e32 v143, 1.0, v114
	v_add_f32_e32 v147, 1.0, v115
	v_rcp_f32_e32 v112, v116
	v_rcp_f32_e32 v113, v117
	v_rcp_f32_e32 v118, v118
	v_rcp_f32_e32 v119, v119
	v_rcp_f32_e32 v114, v130
	v_rcp_f32_e32 v115, v131
	v_rcp_f32_e32 v130, v143
	v_rcp_f32_e32 v131, v147
	v_mul_f32_e32 v124, 0xbfb8aa3b, v124
	v_mul_f32_e32 v120, 0xbfb8aa3b, v120
	v_mul_f32_e32 v125, 0xbfb8aa3b, v125
	v_mul_f32_e32 v121, 0xbfb8aa3b, v121
	v_mul_f32_e32 v122, 0xbfb8aa3b, v122
	v_mul_f32_e32 v123, 0xbfb8aa3b, v123
	v_mul_f32_e32 v126, 0xbfb8aa3b, v126
	v_mul_f32_e32 v127, 0xbfb8aa3b, v127
	v_exp_f32_e32 v124, v124
	v_exp_f32_e32 v120, v120
	v_exp_f32_e32 v125, v125
	v_exp_f32_e32 v121, v121
	v_exp_f32_e32 v122, v122
	v_exp_f32_e32 v123, v123
	v_exp_f32_e32 v126, v126
	v_exp_f32_e32 v127, v127
	v_add_f32_e32 v124, 1.0, v124
	v_add_f32_e32 v125, 1.0, v125
	v_add_f32_e32 v126, 1.0, v126
	v_add_f32_e32 v127, 1.0, v127
	v_rcp_f32_e32 v126, v126
	v_rcp_f32_e32 v127, v127
	v_readlane_b32 s21, v254, 1
	v_readlane_b32 s22, v254, 2
	v_readlane_b32 s23, v254, 3
	v_readlane_b32 s24, v254, 4
	v_readlane_b32 s25, v254, 5
	s_waitcnt vmcnt(3)
	v_lshlrev_b32_e32 v116, 16, v136
	v_and_b32_e32 v117, 0xffff0000, v136
	s_waitcnt vmcnt(2)
	v_lshlrev_b32_e32 v156, 16, v148
	v_and_b32_e32 v157, 0xffff0000, v148
	v_lshlrev_b32_e32 v136, 16, v137
	v_and_b32_e32 v137, 0xffff0000, v137
	v_lshlrev_b32_e32 v148, 16, v149
	v_and_b32_e32 v149, 0xffff0000, v149
	v_lshlrev_b32_e32 v158, 16, v138
	v_and_b32_e32 v159, 0xffff0000, v138
	v_lshlrev_b32_e32 v164, 16, v150
	v_and_b32_e32 v165, 0xffff0000, v150
	v_lshlrev_b32_e32 v138, 16, v139
	v_and_b32_e32 v139, 0xffff0000, v139
	v_lshlrev_b32_e32 v150, 16, v151
	v_and_b32_e32 v151, 0xffff0000, v151
	v_pk_fma_f32 v[116:117], v[112:113], v[156:157], v[116:117]
	v_pk_fma_f32 v[118:119], v[118:119], v[148:149], v[136:137]
	v_pk_fma_f32 v[112:113], v[114:115], v[164:165], v[158:159]
	v_pk_fma_f32 v[114:115], v[130:131], v[150:151], v[138:139]
	global_store_dwordx4 v[154:155], v[116:119], off nt
	global_store_dwordx4 v[154:155], v[112:115], off offset:16 nt
	v_add_f32_e32 v130, 1.0, v120
	v_add_f32_e32 v131, 1.0, v121
	v_add_f32_e32 v140, 1.0, v122
	v_add_f32_e32 v141, 1.0, v123
	v_rcp_f32_e32 v120, v124
	v_rcp_f32_e32 v122, v130
	v_rcp_f32_e32 v121, v125
	v_rcp_f32_e32 v123, v131
	v_rcp_f32_e32 v130, v140
	v_rcp_f32_e32 v131, v141
	v_pk_mul_f32 v[124:125], v[116:117], v[116:117]
	v_pk_mul_f32 v[140:141], v[118:119], v[118:119]
	v_pk_mul_f32 v[152:153], v[112:113], v[112:113]
	v_add_f32_e32 v140, v140, v141
	v_add_f32_e32 v124, v124, v125
	v_pk_mul_f32 v[156:157], v[114:115], v[114:115]
	v_add_f32_e32 v125, v152, v153
	v_add_f32_e32 v124, v124, v140
	v_add_f32_e32 v143, v156, v157
	v_add_f32_e32 v124, v125, v124
	v_add_f32_e32 v143, v143, v124
	s_waitcnt vmcnt(3)
	v_lshlrev_b32_e32 v124, 16, v168
	v_and_b32_e32 v125, 0xffff0000, v168
	s_waitcnt vmcnt(2)
	v_lshlrev_b32_e32 v140, 16, v172
	v_and_b32_e32 v141, 0xffff0000, v172
	v_lshlrev_b32_e32 v136, 16, v169
	v_and_b32_e32 v137, 0xffff0000, v169
	v_lshlrev_b32_e32 v148, 16, v173
	v_and_b32_e32 v149, 0xffff0000, v173
	v_lshlrev_b32_e32 v152, 16, v170
	v_and_b32_e32 v153, 0xffff0000, v170
	v_lshlrev_b32_e32 v156, 16, v174
	v_and_b32_e32 v157, 0xffff0000, v174
	v_lshlrev_b32_e32 v138, 16, v171
	v_and_b32_e32 v139, 0xffff0000, v171
	v_lshlrev_b32_e32 v150, 16, v175
	v_and_b32_e32 v151, 0xffff0000, v175
	v_pk_fma_f32 v[124:125], v[120:121], v[140:141], v[124:125]
	v_pk_fma_f32 v[126:127], v[126:127], v[148:149], v[136:137]
	v_pk_fma_f32 v[120:121], v[122:123], v[156:157], v[152:153]
	v_pk_fma_f32 v[122:123], v[130:131], v[150:151], v[138:139]
	v_pk_mul_f32 v[130:131], v[124:125], v[124:125]
	v_pk_mul_f32 v[136:137], v[126:127], v[126:127]
	v_pk_mul_f32 v[138:139], v[120:121], v[120:121]
	v_add_f32_e32 v136, v136, v137
	v_add_f32_e32 v130, v130, v131
	v_pk_mul_f32 v[140:141], v[122:123], v[122:123]
	v_add_f32_e32 v130, v130, v136
	v_add_f32_e32 v131, v138, v139
	v_add_f32_e32 v140, v140, v141
	v_add_f32_e32 v130, v131, v130
	v_add_f32_e32 v130, v140, v130
	v_add_f32_e32 v130, v143, v130
	ds_bpermute_b32 v131, v133, v130
	global_store_dwordx4 v[154:155], v[124:127], off offset:512 nt
	global_store_dwordx4 v[154:155], v[120:123], off offset:528 nt
	s_waitcnt lgkmcnt(0)
	v_add_f32_e32 v130, v130, v131
	ds_bpermute_b32 v131, v135, v130
	s_and_saveexec_b64 s[18:19], vcc
	s_cbranch_execz .LBB0_1045
	s_waitcnt lgkmcnt(0)
	v_add_f32_e32 v130, v130, v131
	ds_write_b32 v134, v130 offset:256
.LBB0_1045:
	s_or_b64 exec, exec, s[18:19]
	v_or_b32_e32 v130, 32, v128
	s_waitcnt lgkmcnt(0)
	v_ashrrev_i32_e32 v131, 31, v130
	v_lshlrev_b64 v[130:131], 10, v[130:131]
	v_lshl_add_u64 v[130:131], v[130:131], 0, v[144:145]
	v_lshlrev_b64 v[140:141], 1, v[130:131]
	v_lshl_add_u64 v[152:153], s[16:17], 0, v[140:141]
	v_lshl_add_u64 v[140:141], s[12:13], 0, v[140:141]
	global_load_dwordx4 v[136:139], v[152:153], off
	global_load_dwordx4 v[148:151], v[140:141], off
	global_load_dwordx4 v[168:171], v[152:153], off offset:256
	global_load_dwordx4 v[172:175], v[140:141], off offset:256
	v_mul_f32_e32 v88, 0xbfb8aa3b, v88
	v_mul_f32_e32 v89, 0xbfb8aa3b, v89
	v_mul_f32_e32 v90, 0xbfb8aa3b, v90
	v_mul_f32_e32 v91, 0xbfb8aa3b, v91
	v_mul_f32_e32 v84, 0xbfb8aa3b, v84
	v_mul_f32_e32 v85, 0xbfb8aa3b, v85
	v_mul_f32_e32 v86, 0xbfb8aa3b, v86
	v_mul_f32_e32 v87, 0xbfb8aa3b, v87
	v_exp_f32_e32 v88, v88
	v_exp_f32_e32 v89, v89
	v_exp_f32_e32 v90, v90
	v_exp_f32_e32 v91, v91
	v_exp_f32_e32 v84, v84
	v_exp_f32_e32 v85, v85
	v_exp_f32_e32 v86, v86
	v_exp_f32_e32 v87, v87
	v_readlane_b32 s20, v254, 0
	v_readlane_b32 s26, v254, 6
	v_readlane_b32 s27, v254, 7
	v_add_f32_e32 v88, 1.0, v88
	v_add_f32_e32 v89, 1.0, v89
	v_add_f32_e32 v90, 1.0, v90
	v_add_f32_e32 v91, 1.0, v91
	v_lshl_add_u64 v[154:155], v[130:131], 2, s[26:27]
	v_add_f32_e32 v130, 1.0, v84
	v_add_f32_e32 v131, 1.0, v85
	v_add_f32_e32 v143, 1.0, v86
	v_add_f32_e32 v147, 1.0, v87
	v_rcp_f32_e32 v84, v88
	v_rcp_f32_e32 v85, v89
	v_rcp_f32_e32 v90, v90
	v_rcp_f32_e32 v91, v91
	v_rcp_f32_e32 v86, v130
	v_rcp_f32_e32 v87, v131
	v_rcp_f32_e32 v130, v143
	v_rcp_f32_e32 v131, v147
	v_mul_f32_e32 v100, 0xbfb8aa3b, v100
	v_mul_f32_e32 v80, 0xbfb8aa3b, v80
	v_mul_f32_e32 v101, 0xbfb8aa3b, v101
	v_mul_f32_e32 v81, 0xbfb8aa3b, v81
	v_mul_f32_e32 v82, 0xbfb8aa3b, v82
	v_mul_f32_e32 v83, 0xbfb8aa3b, v83
	v_mul_f32_e32 v102, 0xbfb8aa3b, v102
	v_mul_f32_e32 v103, 0xbfb8aa3b, v103
	v_exp_f32_e32 v100, v100
	v_exp_f32_e32 v80, v80
	v_exp_f32_e32 v101, v101
	v_exp_f32_e32 v81, v81
	v_exp_f32_e32 v82, v82
	v_exp_f32_e32 v83, v83
	v_exp_f32_e32 v102, v102
	v_exp_f32_e32 v103, v103
	v_add_f32_e32 v100, 1.0, v100
	v_add_f32_e32 v101, 1.0, v101
	v_add_f32_e32 v102, 1.0, v102
	v_add_f32_e32 v103, 1.0, v103
	v_rcp_f32_e32 v102, v102
	v_rcp_f32_e32 v103, v103
	v_readlane_b32 s21, v254, 1
	v_readlane_b32 s22, v254, 2
	v_readlane_b32 s23, v254, 3
	v_readlane_b32 s24, v254, 4
	v_readlane_b32 s25, v254, 5
	s_waitcnt vmcnt(3)
	v_lshlrev_b32_e32 v88, 16, v136
	v_and_b32_e32 v89, 0xffff0000, v136
	s_waitcnt vmcnt(2)
	v_lshlrev_b32_e32 v156, 16, v148
	v_and_b32_e32 v157, 0xffff0000, v148
	v_lshlrev_b32_e32 v136, 16, v137
	v_and_b32_e32 v137, 0xffff0000, v137
	v_lshlrev_b32_e32 v148, 16, v149
	v_and_b32_e32 v149, 0xffff0000, v149
	v_lshlrev_b32_e32 v158, 16, v138
	v_and_b32_e32 v159, 0xffff0000, v138
	v_lshlrev_b32_e32 v164, 16, v150
	v_and_b32_e32 v165, 0xffff0000, v150
	v_lshlrev_b32_e32 v138, 16, v139
	v_and_b32_e32 v139, 0xffff0000, v139
	v_lshlrev_b32_e32 v150, 16, v151
	v_and_b32_e32 v151, 0xffff0000, v151
	v_pk_fma_f32 v[88:89], v[84:85], v[156:157], v[88:89]
	v_pk_fma_f32 v[90:91], v[90:91], v[148:149], v[136:137]
	v_pk_fma_f32 v[84:85], v[86:87], v[164:165], v[158:159]
	v_pk_fma_f32 v[86:87], v[130:131], v[150:151], v[138:139]
	global_store_dwordx4 v[154:155], v[88:91], off nt
	global_store_dwordx4 v[154:155], v[84:87], off offset:16 nt
	v_add_f32_e32 v130, 1.0, v80
	v_add_f32_e32 v131, 1.0, v81
	v_add_f32_e32 v140, 1.0, v82
	v_add_f32_e32 v141, 1.0, v83
	v_rcp_f32_e32 v80, v100
	v_rcp_f32_e32 v82, v130
	v_rcp_f32_e32 v81, v101
	v_rcp_f32_e32 v83, v131
	v_rcp_f32_e32 v130, v140
	v_rcp_f32_e32 v131, v141
	v_pk_mul_f32 v[100:101], v[88:89], v[88:89]
	v_pk_mul_f32 v[140:141], v[90:91], v[90:91]
	v_pk_mul_f32 v[152:153], v[84:85], v[84:85]
	v_add_f32_e32 v140, v140, v141
	v_add_f32_e32 v100, v100, v101
	v_pk_mul_f32 v[156:157], v[86:87], v[86:87]
	v_add_f32_e32 v101, v152, v153
	v_add_f32_e32 v100, v100, v140
	v_add_f32_e32 v143, v156, v157
	v_add_f32_e32 v100, v101, v100
	v_add_f32_e32 v143, v143, v100
	s_waitcnt vmcnt(3)
	v_lshlrev_b32_e32 v100, 16, v168
	v_and_b32_e32 v101, 0xffff0000, v168
	s_waitcnt vmcnt(2)
	v_lshlrev_b32_e32 v140, 16, v172
	v_and_b32_e32 v141, 0xffff0000, v172
	v_lshlrev_b32_e32 v136, 16, v169
	v_and_b32_e32 v137, 0xffff0000, v169
	v_lshlrev_b32_e32 v148, 16, v173
	v_and_b32_e32 v149, 0xffff0000, v173
	v_lshlrev_b32_e32 v152, 16, v170
	v_and_b32_e32 v153, 0xffff0000, v170
	v_lshlrev_b32_e32 v156, 16, v174
	v_and_b32_e32 v157, 0xffff0000, v174
	v_lshlrev_b32_e32 v138, 16, v171
	v_and_b32_e32 v139, 0xffff0000, v171
	v_lshlrev_b32_e32 v150, 16, v175
	v_and_b32_e32 v151, 0xffff0000, v175
	v_pk_fma_f32 v[100:101], v[80:81], v[140:141], v[100:101]
	v_pk_fma_f32 v[102:103], v[102:103], v[148:149], v[136:137]
	v_pk_fma_f32 v[80:81], v[82:83], v[156:157], v[152:153]
	v_pk_fma_f32 v[82:83], v[130:131], v[150:151], v[138:139]
	v_pk_mul_f32 v[130:131], v[100:101], v[100:101]
	v_pk_mul_f32 v[136:137], v[102:103], v[102:103]
	v_pk_mul_f32 v[138:139], v[80:81], v[80:81]
	v_add_f32_e32 v136, v136, v137
	v_add_f32_e32 v130, v130, v131
	v_pk_mul_f32 v[140:141], v[82:83], v[82:83]
	v_add_f32_e32 v130, v130, v136
	v_add_f32_e32 v131, v138, v139
	v_add_f32_e32 v140, v140, v141
	v_add_f32_e32 v130, v131, v130
	v_add_f32_e32 v130, v140, v130
	v_add_f32_e32 v130, v143, v130
	ds_bpermute_b32 v131, v133, v130
	global_store_dwordx4 v[154:155], v[100:103], off offset:512 nt
	global_store_dwordx4 v[154:155], v[80:83], off offset:528 nt
	s_waitcnt lgkmcnt(0)
	v_add_f32_e32 v130, v130, v131
	ds_bpermute_b32 v131, v135, v130
	s_and_saveexec_b64 s[18:19], vcc
	s_cbranch_execz .LBB0_1047
	s_waitcnt lgkmcnt(0)
	v_add_f32_e32 v130, v130, v131
	ds_write_b32 v134, v130 offset:512
.LBB0_1047:
	s_or_b64 exec, exec, s[18:19]
	v_or_b32_e32 v130, 48, v128
	s_waitcnt lgkmcnt(0)
	v_ashrrev_i32_e32 v131, 31, v130
	v_lshlrev_b64 v[130:131], 10, v[130:131]
	v_lshl_add_u64 v[130:131], v[130:131], 0, v[144:145]
	v_lshlrev_b64 v[140:141], 1, v[130:131]
	v_lshl_add_u64 v[152:153], s[16:17], 0, v[140:141]
	v_lshl_add_u64 v[140:141], s[12:13], 0, v[140:141]
	global_load_dwordx4 v[136:139], v[152:153], off
	global_load_dwordx4 v[148:151], v[140:141], off
	global_load_dwordx4 v[168:171], v[152:153], off offset:256
	global_load_dwordx4 v[172:175], v[140:141], off offset:256
	v_mul_f32_e32 v108, 0xbfb8aa3b, v108
	v_mul_f32_e32 v109, 0xbfb8aa3b, v109
	v_mul_f32_e32 v110, 0xbfb8aa3b, v110
	v_mul_f32_e32 v111, 0xbfb8aa3b, v111
	v_mul_f32_e32 v104, 0xbfb8aa3b, v104
	v_mul_f32_e32 v105, 0xbfb8aa3b, v105
	v_mul_f32_e32 v106, 0xbfb8aa3b, v106
	v_mul_f32_e32 v107, 0xbfb8aa3b, v107
	v_exp_f32_e32 v108, v108
	v_exp_f32_e32 v109, v109
	v_exp_f32_e32 v110, v110
	v_exp_f32_e32 v111, v111
	v_exp_f32_e32 v104, v104
	v_exp_f32_e32 v105, v105
	v_exp_f32_e32 v106, v106
	v_exp_f32_e32 v107, v107
	v_readlane_b32 s20, v254, 0
	v_readlane_b32 s26, v254, 6
	v_readlane_b32 s27, v254, 7
	v_add_f32_e32 v108, 1.0, v108
	v_add_f32_e32 v109, 1.0, v109
	v_add_f32_e32 v110, 1.0, v110
	v_add_f32_e32 v111, 1.0, v111
	v_lshl_add_u64 v[154:155], v[130:131], 2, s[26:27]
	v_add_f32_e32 v130, 1.0, v104
	v_add_f32_e32 v131, 1.0, v105
	v_add_f32_e32 v143, 1.0, v106
	v_add_f32_e32 v147, 1.0, v107
	v_rcp_f32_e32 v104, v108
	v_rcp_f32_e32 v105, v109
	v_rcp_f32_e32 v110, v110
	v_rcp_f32_e32 v111, v111
	v_rcp_f32_e32 v106, v130
	v_rcp_f32_e32 v107, v131
	v_rcp_f32_e32 v130, v143
	v_rcp_f32_e32 v131, v147
	v_mul_f32_e32 v68, 0xbfb8aa3b, v68
	v_mul_f32_e32 v64, 0xbfb8aa3b, v64
	v_mul_f32_e32 v69, 0xbfb8aa3b, v69
	v_mul_f32_e32 v65, 0xbfb8aa3b, v65
	v_mul_f32_e32 v66, 0xbfb8aa3b, v66
	v_mul_f32_e32 v67, 0xbfb8aa3b, v67
	v_mul_f32_e32 v70, 0xbfb8aa3b, v70
	v_mul_f32_e32 v71, 0xbfb8aa3b, v71
	v_exp_f32_e32 v68, v68
	v_exp_f32_e32 v64, v64
	v_exp_f32_e32 v69, v69
	v_exp_f32_e32 v65, v65
	v_exp_f32_e32 v66, v66
	v_exp_f32_e32 v67, v67
	v_exp_f32_e32 v70, v70
	v_exp_f32_e32 v71, v71
	v_add_f32_e32 v68, 1.0, v68
	v_add_f32_e32 v69, 1.0, v69
	v_add_f32_e32 v70, 1.0, v70
	v_add_f32_e32 v71, 1.0, v71
	v_rcp_f32_e32 v70, v70
	v_rcp_f32_e32 v71, v71
	v_readlane_b32 s21, v254, 1
	v_readlane_b32 s22, v254, 2
	v_readlane_b32 s23, v254, 3
	v_readlane_b32 s24, v254, 4
	v_readlane_b32 s25, v254, 5
	s_waitcnt vmcnt(3)
	v_lshlrev_b32_e32 v108, 16, v136
	v_and_b32_e32 v109, 0xffff0000, v136
	s_waitcnt vmcnt(2)
	v_lshlrev_b32_e32 v156, 16, v148
	v_and_b32_e32 v157, 0xffff0000, v148
	v_lshlrev_b32_e32 v136, 16, v137
	v_and_b32_e32 v137, 0xffff0000, v137
	v_lshlrev_b32_e32 v148, 16, v149
	v_and_b32_e32 v149, 0xffff0000, v149
	v_lshlrev_b32_e32 v158, 16, v138
	v_and_b32_e32 v159, 0xffff0000, v138
	v_lshlrev_b32_e32 v164, 16, v150
	v_and_b32_e32 v165, 0xffff0000, v150
	v_lshlrev_b32_e32 v138, 16, v139
	v_and_b32_e32 v139, 0xffff0000, v139
	v_lshlrev_b32_e32 v150, 16, v151
	v_and_b32_e32 v151, 0xffff0000, v151
	v_pk_fma_f32 v[108:109], v[104:105], v[156:157], v[108:109]
	v_pk_fma_f32 v[110:111], v[110:111], v[148:149], v[136:137]
	v_pk_fma_f32 v[104:105], v[106:107], v[164:165], v[158:159]
	v_pk_fma_f32 v[106:107], v[130:131], v[150:151], v[138:139]
	global_store_dwordx4 v[154:155], v[108:111], off nt
	global_store_dwordx4 v[154:155], v[104:107], off offset:16 nt
	v_add_f32_e32 v130, 1.0, v64
	v_add_f32_e32 v131, 1.0, v65
	v_add_f32_e32 v140, 1.0, v66
	v_add_f32_e32 v141, 1.0, v67
	v_rcp_f32_e32 v64, v68
	v_rcp_f32_e32 v66, v130
	v_rcp_f32_e32 v65, v69
	v_rcp_f32_e32 v67, v131
	v_rcp_f32_e32 v130, v140
	v_rcp_f32_e32 v131, v141
	v_pk_mul_f32 v[68:69], v[108:109], v[108:109]
	v_pk_mul_f32 v[140:141], v[110:111], v[110:111]
	v_pk_mul_f32 v[152:153], v[104:105], v[104:105]
	v_add_f32_e32 v140, v140, v141
	v_add_f32_e32 v68, v68, v69
	v_pk_mul_f32 v[156:157], v[106:107], v[106:107]
	v_add_f32_e32 v69, v152, v153
	v_add_f32_e32 v68, v68, v140
	v_add_f32_e32 v143, v156, v157
	v_add_f32_e32 v68, v69, v68
	v_add_f32_e32 v143, v143, v68
	s_waitcnt vmcnt(3)
	v_lshlrev_b32_e32 v68, 16, v168
	v_and_b32_e32 v69, 0xffff0000, v168
	s_waitcnt vmcnt(2)
	v_lshlrev_b32_e32 v140, 16, v172
	v_and_b32_e32 v141, 0xffff0000, v172
	v_lshlrev_b32_e32 v136, 16, v169
	v_and_b32_e32 v137, 0xffff0000, v169
	v_lshlrev_b32_e32 v148, 16, v173
	v_and_b32_e32 v149, 0xffff0000, v173
	v_lshlrev_b32_e32 v152, 16, v170
	v_and_b32_e32 v153, 0xffff0000, v170
	v_lshlrev_b32_e32 v156, 16, v174
	v_and_b32_e32 v157, 0xffff0000, v174
	v_lshlrev_b32_e32 v138, 16, v171
	v_and_b32_e32 v139, 0xffff0000, v171
	v_lshlrev_b32_e32 v150, 16, v175
	v_and_b32_e32 v151, 0xffff0000, v175
	v_pk_fma_f32 v[68:69], v[64:65], v[140:141], v[68:69]
	v_pk_fma_f32 v[70:71], v[70:71], v[148:149], v[136:137]
	v_pk_fma_f32 v[64:65], v[66:67], v[156:157], v[152:153]
	v_pk_fma_f32 v[66:67], v[130:131], v[150:151], v[138:139]
	v_pk_mul_f32 v[130:131], v[68:69], v[68:69]
	v_pk_mul_f32 v[136:137], v[70:71], v[70:71]
	v_pk_mul_f32 v[138:139], v[64:65], v[64:65]
	v_add_f32_e32 v136, v136, v137
	v_add_f32_e32 v130, v130, v131
	v_pk_mul_f32 v[140:141], v[66:67], v[66:67]
	v_add_f32_e32 v130, v130, v136
	v_add_f32_e32 v131, v138, v139
	v_add_f32_e32 v140, v140, v141
	v_add_f32_e32 v130, v131, v130
	v_add_f32_e32 v130, v140, v130
	v_add_f32_e32 v130, v143, v130
	ds_bpermute_b32 v131, v133, v130
	global_store_dwordx4 v[154:155], v[68:71], off offset:512 nt
	global_store_dwordx4 v[154:155], v[64:67], off offset:528 nt
	s_waitcnt lgkmcnt(0)
	v_add_f32_e32 v130, v130, v131
	ds_bpermute_b32 v131, v135, v130
	s_and_saveexec_b64 s[18:19], vcc
	s_cbranch_execz .LBB0_1049
	s_waitcnt lgkmcnt(0)
	v_add_f32_e32 v130, v130, v131
	ds_write_b32 v134, v130 offset:768
.LBB0_1049:
	s_or_b64 exec, exec, s[18:19]
	s_waitcnt lgkmcnt(0)
	v_lshlrev_b64 v[130:131], 10, v[128:129]
	v_lshl_add_u64 v[130:131], v[130:131], 0, v[144:145]
	s_mov_b64 s[18:19], 0x20000
	v_lshl_add_u64 v[140:141], v[130:131], 0, s[18:19]
	v_lshlrev_b64 v[148:149], 1, v[140:141]
	v_lshl_add_u64 v[152:153], s[16:17], 0, v[148:149]
	v_lshl_add_u64 v[154:155], s[12:13], 0, v[148:149]
	global_load_dwordx4 v[136:139], v[152:153], off
	global_load_dwordx4 v[148:151], v[154:155], off
	global_load_dwordx4 v[168:171], v[152:153], off offset:256
	global_load_dwordx4 v[172:175], v[154:155], off offset:256
	v_mul_f32_e32 v60, 0xbfb8aa3b, v60
	v_mul_f32_e32 v61, 0xbfb8aa3b, v61
	v_mul_f32_e32 v62, 0xbfb8aa3b, v62
	v_mul_f32_e32 v63, 0xbfb8aa3b, v63
	v_mul_f32_e32 v56, 0xbfb8aa3b, v56
	v_mul_f32_e32 v57, 0xbfb8aa3b, v57
	v_mul_f32_e32 v58, 0xbfb8aa3b, v58
	v_mul_f32_e32 v59, 0xbfb8aa3b, v59
	v_exp_f32_e32 v60, v60
	v_exp_f32_e32 v61, v61
	v_exp_f32_e32 v62, v62
	v_exp_f32_e32 v63, v63
	v_exp_f32_e32 v56, v56
	v_exp_f32_e32 v57, v57
	v_exp_f32_e32 v58, v58
	v_exp_f32_e32 v59, v59
	v_add_f32_e32 v60, 1.0, v60
	v_add_f32_e32 v61, 1.0, v61
	v_add_f32_e32 v62, 1.0, v62
	v_add_f32_e32 v63, 1.0, v63
	v_add_f32_e32 v143, 1.0, v56
	v_add_f32_e32 v147, 1.0, v57
	v_add_f32_e32 v156, 1.0, v58
	v_add_f32_e32 v157, 1.0, v59
	v_rcp_f32_e32 v56, v60
	v_rcp_f32_e32 v57, v61
	v_rcp_f32_e32 v62, v62
	v_rcp_f32_e32 v63, v63
	v_rcp_f32_e32 v58, v143
	v_rcp_f32_e32 v59, v147
	v_rcp_f32_e32 v156, v156
	v_rcp_f32_e32 v157, v157
	v_readlane_b32 s20, v254, 0
	v_readlane_b32 s26, v254, 6
	v_readlane_b32 s27, v254, 7
	v_mul_f32_e32 v52, 0xbfb8aa3b, v52
	v_mul_f32_e32 v53, 0xbfb8aa3b, v53
	v_lshl_add_u64 v[140:141], v[140:141], 2, s[26:27]
	v_mul_f32_e32 v48, 0xbfb8aa3b, v48
	v_mul_f32_e32 v49, 0xbfb8aa3b, v49
	v_mul_f32_e32 v54, 0xbfb8aa3b, v54
	v_mul_f32_e32 v55, 0xbfb8aa3b, v55
	v_exp_f32_e32 v52, v52
	v_exp_f32_e32 v53, v53
	v_mul_f32_e32 v50, 0xbfb8aa3b, v50
	v_mul_f32_e32 v51, 0xbfb8aa3b, v51
	v_exp_f32_e32 v48, v48
	v_exp_f32_e32 v49, v49
	v_exp_f32_e32 v54, v54
	v_exp_f32_e32 v55, v55
	v_exp_f32_e32 v50, v50
	v_exp_f32_e32 v51, v51
	v_add_f32_e32 v52, 1.0, v52
	v_add_f32_e32 v53, 1.0, v53
	v_add_f32_e32 v143, 1.0, v48
	v_add_f32_e32 v147, 1.0, v49
	v_add_f32_e32 v54, 1.0, v54
	v_add_f32_e32 v55, 1.0, v55
	v_rcp_f32_e32 v48, v52
	v_rcp_f32_e32 v49, v53
	v_rcp_f32_e32 v54, v54
	v_rcp_f32_e32 v55, v55
	v_readlane_b32 s21, v254, 1
	v_readlane_b32 s22, v254, 2
	v_readlane_b32 s23, v254, 3
	v_readlane_b32 s24, v254, 4
	v_readlane_b32 s25, v254, 5
	s_waitcnt vmcnt(3)
	v_lshlrev_b32_e32 v60, 16, v136
	v_and_b32_e32 v61, 0xffff0000, v136
	s_waitcnt vmcnt(2)
	v_lshlrev_b32_e32 v158, 16, v148
	v_and_b32_e32 v159, 0xffff0000, v148
	v_lshlrev_b32_e32 v136, 16, v137
	v_and_b32_e32 v137, 0xffff0000, v137
	v_lshlrev_b32_e32 v148, 16, v149
	v_and_b32_e32 v149, 0xffff0000, v149
	v_lshlrev_b32_e32 v164, 16, v138
	v_and_b32_e32 v165, 0xffff0000, v138
	v_lshlrev_b32_e32 v166, 16, v150
	v_and_b32_e32 v167, 0xffff0000, v150
	v_lshlrev_b32_e32 v138, 16, v139
	v_and_b32_e32 v139, 0xffff0000, v139
	v_lshlrev_b32_e32 v150, 16, v151
	v_and_b32_e32 v151, 0xffff0000, v151
	v_pk_fma_f32 v[60:61], v[56:57], v[158:159], v[60:61]
	v_pk_fma_f32 v[62:63], v[62:63], v[148:149], v[136:137]
	v_pk_fma_f32 v[56:57], v[58:59], v[166:167], v[164:165]
	v_pk_fma_f32 v[58:59], v[156:157], v[150:151], v[138:139]
	global_store_dwordx4 v[140:141], v[60:63], off nt
	global_store_dwordx4 v[140:141], v[56:59], off offset:16 nt
	v_pk_mul_f32 v[52:53], v[60:61], v[60:61]
	v_pk_mul_f32 v[154:155], v[62:63], v[62:63]
	v_add_f32_e32 v152, 1.0, v50
	v_add_f32_e32 v153, 1.0, v51
	v_rcp_f32_e32 v50, v143
	v_pk_mul_f32 v[156:157], v[56:57], v[56:57]
	v_add_f32_e32 v143, v154, v155
	v_add_f32_e32 v52, v52, v53
	v_rcp_f32_e32 v51, v147
	v_rcp_f32_e32 v152, v152
	v_rcp_f32_e32 v153, v153
	v_pk_mul_f32 v[158:159], v[58:59], v[58:59]
	v_add_f32_e32 v53, v156, v157
	v_add_f32_e32 v52, v52, v143
	v_add_f32_e32 v147, v158, v159
	v_add_f32_e32 v52, v53, v52
	v_add_f32_e32 v143, v147, v52
	s_waitcnt vmcnt(3)
	v_lshlrev_b32_e32 v52, 16, v168
	v_and_b32_e32 v53, 0xffff0000, v168
	s_waitcnt vmcnt(2)
	v_lshlrev_b32_e32 v154, 16, v172
	v_and_b32_e32 v155, 0xffff0000, v172
	v_lshlrev_b32_e32 v136, 16, v169
	v_and_b32_e32 v137, 0xffff0000, v169
	v_lshlrev_b32_e32 v148, 16, v173
	v_and_b32_e32 v149, 0xffff0000, v173
	v_lshlrev_b32_e32 v156, 16, v170
	v_and_b32_e32 v157, 0xffff0000, v170
	v_lshlrev_b32_e32 v158, 16, v174
	v_and_b32_e32 v159, 0xffff0000, v174
	v_lshlrev_b32_e32 v138, 16, v171
	v_and_b32_e32 v139, 0xffff0000, v171
	v_lshlrev_b32_e32 v150, 16, v175
	v_and_b32_e32 v151, 0xffff0000, v175
	v_pk_fma_f32 v[52:53], v[48:49], v[154:155], v[52:53]
	v_pk_fma_f32 v[54:55], v[54:55], v[148:149], v[136:137]
	v_pk_fma_f32 v[48:49], v[50:51], v[158:159], v[156:157]
	v_pk_fma_f32 v[50:51], v[152:153], v[150:151], v[138:139]
	v_pk_mul_f32 v[136:137], v[52:53], v[52:53]
	v_pk_mul_f32 v[138:139], v[54:55], v[54:55]
	v_pk_mul_f32 v[148:149], v[48:49], v[48:49]
	v_add_f32_e32 v138, v138, v139
	v_add_f32_e32 v136, v136, v137
	v_pk_mul_f32 v[150:151], v[50:51], v[50:51]
	v_add_f32_e32 v137, v148, v149
	v_add_f32_e32 v136, v136, v138
	v_add_f32_e32 v136, v137, v136
	v_add_f32_e32 v137, v150, v151
	v_add_f32_e32 v136, v137, v136
	v_add_f32_e32 v136, v143, v136
	ds_bpermute_b32 v137, v133, v136
	v_add_u32_e32 v148, 0x80, v146
	global_store_dwordx4 v[140:141], v[52:55], off offset:512 nt
	global_store_dwordx4 v[140:141], v[48:51], off offset:528 nt
	s_waitcnt lgkmcnt(0)
	v_add_f32_e32 v136, v136, v137
	ds_bpermute_b32 v137, v135, v136
	s_and_saveexec_b64 s[18:19], vcc
	s_cbranch_execz .LBB0_1051
	v_lshl_add_u32 v138, v148, 4, s3
	s_waitcnt lgkmcnt(0)
	v_add_f32_e32 v136, v136, v137
	ds_write_b32 v138, v136
.LBB0_1051:
	s_or_b64 exec, exec, s[18:19]
	s_mov_b64 s[18:19], 0x24000
	v_lshl_add_u64 v[130:131], v[130:131], 0, s[18:19]
	v_lshlrev_b64 v[140:141], 1, v[130:131]
	v_lshl_add_u64 v[154:155], s[16:17], 0, v[140:141]
	v_lshl_add_u64 v[140:141], s[12:13], 0, v[140:141]
	s_waitcnt lgkmcnt(0)
	global_load_dwordx4 v[136:139], v[154:155], off
	global_load_dwordx4 v[150:153], v[140:141], off
	global_load_dwordx4 v[168:171], v[154:155], off offset:256
	global_load_dwordx4 v[172:175], v[140:141], off offset:256
	v_mul_f32_e32 v44, 0xbfb8aa3b, v44
	v_mul_f32_e32 v45, 0xbfb8aa3b, v45
	v_mul_f32_e32 v46, 0xbfb8aa3b, v46
	v_mul_f32_e32 v47, 0xbfb8aa3b, v47
	v_mul_f32_e32 v40, 0xbfb8aa3b, v40
	v_mul_f32_e32 v41, 0xbfb8aa3b, v41
	v_mul_f32_e32 v42, 0xbfb8aa3b, v42
	v_mul_f32_e32 v43, 0xbfb8aa3b, v43
	v_exp_f32_e32 v44, v44
	v_exp_f32_e32 v45, v45
	v_exp_f32_e32 v46, v46
	v_exp_f32_e32 v47, v47
	v_exp_f32_e32 v40, v40
	v_exp_f32_e32 v41, v41
	v_exp_f32_e32 v42, v42
	v_exp_f32_e32 v43, v43
	v_readlane_b32 s20, v254, 0
	v_readlane_b32 s26, v254, 6
	v_readlane_b32 s27, v254, 7
	v_add_f32_e32 v44, 1.0, v44
	v_add_f32_e32 v45, 1.0, v45
	v_add_f32_e32 v46, 1.0, v46
	v_add_f32_e32 v47, 1.0, v47
	v_lshl_add_u64 v[156:157], v[130:131], 2, s[26:27]
	v_add_f32_e32 v130, 1.0, v40
	v_add_f32_e32 v131, 1.0, v41
	v_add_f32_e32 v143, 1.0, v42
	v_add_f32_e32 v147, 1.0, v43
	v_rcp_f32_e32 v40, v44
	v_rcp_f32_e32 v41, v45
	v_rcp_f32_e32 v46, v46
	v_rcp_f32_e32 v47, v47
	v_rcp_f32_e32 v42, v130
	v_rcp_f32_e32 v43, v131
	v_rcp_f32_e32 v130, v143
	v_rcp_f32_e32 v131, v147
	v_mul_f32_e32 v36, 0xbfb8aa3b, v36
	v_mul_f32_e32 v32, 0xbfb8aa3b, v32
	v_mul_f32_e32 v37, 0xbfb8aa3b, v37
	v_mul_f32_e32 v33, 0xbfb8aa3b, v33
	v_mul_f32_e32 v34, 0xbfb8aa3b, v34
	v_mul_f32_e32 v35, 0xbfb8aa3b, v35
	v_mul_f32_e32 v38, 0xbfb8aa3b, v38
	v_mul_f32_e32 v39, 0xbfb8aa3b, v39
	v_exp_f32_e32 v36, v36
	v_exp_f32_e32 v32, v32
	v_exp_f32_e32 v37, v37
	v_exp_f32_e32 v33, v33
	v_exp_f32_e32 v34, v34
	v_exp_f32_e32 v35, v35
	v_exp_f32_e32 v38, v38
	v_exp_f32_e32 v39, v39
	v_add_f32_e32 v36, 1.0, v36
	v_add_f32_e32 v37, 1.0, v37
	v_add_f32_e32 v38, 1.0, v38
	v_add_f32_e32 v39, 1.0, v39
	v_rcp_f32_e32 v38, v38
	v_rcp_f32_e32 v39, v39
	v_readlane_b32 s21, v254, 1
	v_readlane_b32 s22, v254, 2
	v_readlane_b32 s23, v254, 3
	v_readlane_b32 s24, v254, 4
	v_readlane_b32 s25, v254, 5
	s_waitcnt vmcnt(3)
	v_lshlrev_b32_e32 v44, 16, v136
	v_and_b32_e32 v45, 0xffff0000, v136
	s_waitcnt vmcnt(2)
	v_lshlrev_b32_e32 v158, 16, v150
	v_and_b32_e32 v159, 0xffff0000, v150
	v_lshlrev_b32_e32 v136, 16, v137
	v_and_b32_e32 v137, 0xffff0000, v137
	v_lshlrev_b32_e32 v150, 16, v151
	v_and_b32_e32 v151, 0xffff0000, v151
	v_lshlrev_b32_e32 v164, 16, v138
	v_and_b32_e32 v165, 0xffff0000, v138
	v_lshlrev_b32_e32 v166, 16, v152
	v_and_b32_e32 v167, 0xffff0000, v152
	v_lshlrev_b32_e32 v138, 16, v139
	v_and_b32_e32 v139, 0xffff0000, v139
	v_lshlrev_b32_e32 v152, 16, v153
	v_and_b32_e32 v153, 0xffff0000, v153
	v_pk_fma_f32 v[44:45], v[40:41], v[158:159], v[44:45]
	v_pk_fma_f32 v[46:47], v[46:47], v[150:151], v[136:137]
	v_pk_fma_f32 v[40:41], v[42:43], v[166:167], v[164:165]
	v_pk_fma_f32 v[42:43], v[130:131], v[152:153], v[138:139]
	global_store_dwordx4 v[156:157], v[44:47], off nt
	global_store_dwordx4 v[156:157], v[40:43], off offset:16 nt
	v_add_f32_e32 v130, 1.0, v32
	v_add_f32_e32 v131, 1.0, v33
	v_add_f32_e32 v140, 1.0, v34
	v_add_f32_e32 v141, 1.0, v35
	v_rcp_f32_e32 v32, v36
	v_rcp_f32_e32 v34, v130
	v_rcp_f32_e32 v33, v37
	v_rcp_f32_e32 v35, v131
	v_rcp_f32_e32 v130, v140
	v_rcp_f32_e32 v131, v141
	v_pk_mul_f32 v[36:37], v[44:45], v[44:45]
	v_pk_mul_f32 v[140:141], v[46:47], v[46:47]
	v_pk_mul_f32 v[154:155], v[40:41], v[40:41]
	v_add_f32_e32 v140, v140, v141
	v_add_f32_e32 v36, v36, v37
	v_pk_mul_f32 v[158:159], v[42:43], v[42:43]
	v_add_f32_e32 v37, v154, v155
	v_add_f32_e32 v36, v36, v140
	v_add_f32_e32 v141, v158, v159
	v_add_f32_e32 v36, v37, v36
	v_add_f32_e32 v143, v141, v36
	s_waitcnt vmcnt(3)
	v_lshlrev_b32_e32 v36, 16, v168
	v_and_b32_e32 v37, 0xffff0000, v168
	s_waitcnt vmcnt(2)
	v_lshlrev_b32_e32 v140, 16, v172
	v_and_b32_e32 v141, 0xffff0000, v172
	v_lshlrev_b32_e32 v136, 16, v169
	v_and_b32_e32 v137, 0xffff0000, v169
	v_lshlrev_b32_e32 v150, 16, v173
	v_and_b32_e32 v151, 0xffff0000, v173
	v_lshlrev_b32_e32 v154, 16, v170
	v_and_b32_e32 v155, 0xffff0000, v170
	v_lshlrev_b32_e32 v158, 16, v174
	v_and_b32_e32 v159, 0xffff0000, v174
	v_lshlrev_b32_e32 v138, 16, v171
	v_and_b32_e32 v139, 0xffff0000, v171
	v_lshlrev_b32_e32 v152, 16, v175
	v_and_b32_e32 v153, 0xffff0000, v175
	v_pk_fma_f32 v[36:37], v[32:33], v[140:141], v[36:37]
	v_pk_fma_f32 v[38:39], v[38:39], v[150:151], v[136:137]
	v_pk_fma_f32 v[32:33], v[34:35], v[158:159], v[154:155]
	v_pk_fma_f32 v[34:35], v[130:131], v[152:153], v[138:139]
	v_pk_mul_f32 v[130:131], v[36:37], v[36:37]
	v_pk_mul_f32 v[136:137], v[38:39], v[38:39]
	v_pk_mul_f32 v[138:139], v[32:33], v[32:33]
	v_add_f32_e32 v136, v136, v137
	v_add_f32_e32 v130, v130, v131
	v_pk_mul_f32 v[140:141], v[34:35], v[34:35]
	v_add_f32_e32 v131, v138, v139
	v_add_f32_e32 v130, v130, v136
	v_add_f32_e32 v130, v131, v130
	v_add_f32_e32 v131, v140, v141
	v_add_f32_e32 v130, v131, v130
	v_add_f32_e32 v130, v143, v130
	ds_bpermute_b32 v131, v133, v130
	global_store_dwordx4 v[156:157], v[36:39], off offset:512 nt
	global_store_dwordx4 v[156:157], v[32:35], off offset:528 nt
	s_waitcnt lgkmcnt(0)
	v_add_f32_e32 v130, v130, v131
	ds_bpermute_b32 v131, v135, v130
	s_and_saveexec_b64 s[18:19], vcc
	s_cbranch_execz .LBB0_1053
	s_waitcnt lgkmcnt(0)
	v_add_f32_e32 v130, v130, v131
	ds_write_b32 v134, v130 offset:2304
.LBB0_1053:
	s_or_b64 exec, exec, s[18:19]
	v_lshlrev_b64 v[128:129], 10, v[128:129]
	v_lshl_add_u64 v[128:129], v[128:129], 0, v[144:145]
	s_mov_b64 s[18:19], 0x28000
	s_waitcnt lgkmcnt(0)
	v_lshl_add_u64 v[130:131], v[128:129], 0, s[18:19]
	v_lshlrev_b64 v[140:141], 1, v[130:131]
	v_lshl_add_u64 v[154:155], s[16:17], 0, v[140:141]
	v_lshl_add_u64 v[140:141], s[12:13], 0, v[140:141]
	global_load_dwordx4 v[136:139], v[154:155], off
	global_load_dwordx4 v[150:153], v[140:141], off
	global_load_dwordx4 v[168:171], v[154:155], off offset:256
	global_load_dwordx4 v[172:175], v[140:141], off offset:256
	v_mul_f32_e32 v28, 0xbfb8aa3b, v28
	v_mul_f32_e32 v29, 0xbfb8aa3b, v29
	v_mul_f32_e32 v30, 0xbfb8aa3b, v30
	v_mul_f32_e32 v31, 0xbfb8aa3b, v31
	v_mul_f32_e32 v24, 0xbfb8aa3b, v24
	v_mul_f32_e32 v25, 0xbfb8aa3b, v25
	v_mul_f32_e32 v26, 0xbfb8aa3b, v26
	v_mul_f32_e32 v27, 0xbfb8aa3b, v27
	v_exp_f32_e32 v28, v28
	v_exp_f32_e32 v29, v29
	v_exp_f32_e32 v30, v30
	v_exp_f32_e32 v31, v31
	v_exp_f32_e32 v24, v24
	v_exp_f32_e32 v25, v25
	v_exp_f32_e32 v26, v26
	v_exp_f32_e32 v27, v27
	v_readlane_b32 s20, v254, 0
	v_readlane_b32 s26, v254, 6
	v_readlane_b32 s27, v254, 7
	v_add_f32_e32 v28, 1.0, v28
	v_add_f32_e32 v29, 1.0, v29
	v_add_f32_e32 v30, 1.0, v30
	v_add_f32_e32 v31, 1.0, v31
	v_lshl_add_u64 v[156:157], v[130:131], 2, s[26:27]
	v_add_f32_e32 v130, 1.0, v24
	v_add_f32_e32 v131, 1.0, v25
	v_add_f32_e32 v143, 1.0, v26
	v_add_f32_e32 v147, 1.0, v27
	v_rcp_f32_e32 v24, v28
	v_rcp_f32_e32 v25, v29
	v_rcp_f32_e32 v30, v30
	v_rcp_f32_e32 v31, v31
	v_rcp_f32_e32 v26, v130
	v_rcp_f32_e32 v27, v131
	v_rcp_f32_e32 v130, v143
	v_rcp_f32_e32 v131, v147
	v_mul_f32_e32 v20, 0xbfb8aa3b, v20
	v_mul_f32_e32 v16, 0xbfb8aa3b, v16
	v_mul_f32_e32 v21, 0xbfb8aa3b, v21
	v_mul_f32_e32 v17, 0xbfb8aa3b, v17
	v_mul_f32_e32 v18, 0xbfb8aa3b, v18
	v_mul_f32_e32 v19, 0xbfb8aa3b, v19
	v_mul_f32_e32 v22, 0xbfb8aa3b, v22
	v_mul_f32_e32 v23, 0xbfb8aa3b, v23
	v_exp_f32_e32 v20, v20
	v_exp_f32_e32 v16, v16
	v_exp_f32_e32 v21, v21
	v_exp_f32_e32 v17, v17
	v_exp_f32_e32 v18, v18
	v_exp_f32_e32 v19, v19
	v_exp_f32_e32 v22, v22
	v_exp_f32_e32 v23, v23
	v_add_f32_e32 v20, 1.0, v20
	v_add_f32_e32 v21, 1.0, v21
	v_add_f32_e32 v22, 1.0, v22
	v_add_f32_e32 v23, 1.0, v23
	v_rcp_f32_e32 v22, v22
	v_rcp_f32_e32 v23, v23
	v_readlane_b32 s21, v254, 1
	v_readlane_b32 s22, v254, 2
	v_readlane_b32 s23, v254, 3
	v_readlane_b32 s24, v254, 4
	v_readlane_b32 s25, v254, 5
	s_waitcnt vmcnt(3)
	v_lshlrev_b32_e32 v28, 16, v136
	v_and_b32_e32 v29, 0xffff0000, v136
	s_waitcnt vmcnt(2)
	v_lshlrev_b32_e32 v158, 16, v150
	v_and_b32_e32 v159, 0xffff0000, v150
	v_lshlrev_b32_e32 v136, 16, v137
	v_and_b32_e32 v137, 0xffff0000, v137
	v_lshlrev_b32_e32 v150, 16, v151
	v_and_b32_e32 v151, 0xffff0000, v151
	v_lshlrev_b32_e32 v164, 16, v138
	v_and_b32_e32 v165, 0xffff0000, v138
	v_lshlrev_b32_e32 v166, 16, v152
	v_and_b32_e32 v167, 0xffff0000, v152
	v_lshlrev_b32_e32 v138, 16, v139
	v_and_b32_e32 v139, 0xffff0000, v139
	v_lshlrev_b32_e32 v152, 16, v153
	v_and_b32_e32 v153, 0xffff0000, v153
	v_pk_fma_f32 v[28:29], v[24:25], v[158:159], v[28:29]
	v_pk_fma_f32 v[30:31], v[30:31], v[150:151], v[136:137]
	v_pk_fma_f32 v[24:25], v[26:27], v[166:167], v[164:165]
	v_pk_fma_f32 v[26:27], v[130:131], v[152:153], v[138:139]
	global_store_dwordx4 v[156:157], v[28:31], off nt
	global_store_dwordx4 v[156:157], v[24:27], off offset:16 nt
	v_add_f32_e32 v130, 1.0, v16
	v_add_f32_e32 v131, 1.0, v17
	v_add_f32_e32 v140, 1.0, v18
	v_add_f32_e32 v141, 1.0, v19
	v_rcp_f32_e32 v16, v20
	v_rcp_f32_e32 v18, v130
	v_rcp_f32_e32 v17, v21
	v_rcp_f32_e32 v19, v131
	v_rcp_f32_e32 v130, v140
	v_rcp_f32_e32 v131, v141
	v_pk_mul_f32 v[20:21], v[28:29], v[28:29]
	v_pk_mul_f32 v[140:141], v[30:31], v[30:31]
	v_pk_mul_f32 v[154:155], v[24:25], v[24:25]
	v_add_f32_e32 v140, v140, v141
	v_add_f32_e32 v20, v20, v21
	v_pk_mul_f32 v[158:159], v[26:27], v[26:27]
	v_add_f32_e32 v21, v154, v155
	v_add_f32_e32 v20, v20, v140
	v_add_f32_e32 v141, v158, v159
	v_add_f32_e32 v20, v21, v20
	v_add_f32_e32 v143, v141, v20
	s_waitcnt vmcnt(3)
	v_lshlrev_b32_e32 v20, 16, v168
	v_and_b32_e32 v21, 0xffff0000, v168
	s_waitcnt vmcnt(2)
	v_lshlrev_b32_e32 v140, 16, v172
	v_and_b32_e32 v141, 0xffff0000, v172
	v_lshlrev_b32_e32 v136, 16, v169
	v_and_b32_e32 v137, 0xffff0000, v169
	v_lshlrev_b32_e32 v150, 16, v173
	v_and_b32_e32 v151, 0xffff0000, v173
	v_lshlrev_b32_e32 v154, 16, v170
	v_and_b32_e32 v155, 0xffff0000, v170
	v_lshlrev_b32_e32 v158, 16, v174
	v_and_b32_e32 v159, 0xffff0000, v174
	v_lshlrev_b32_e32 v138, 16, v171
	v_and_b32_e32 v139, 0xffff0000, v171
	v_lshlrev_b32_e32 v152, 16, v175
	v_and_b32_e32 v153, 0xffff0000, v175
	v_pk_fma_f32 v[20:21], v[16:17], v[140:141], v[20:21]
	v_pk_fma_f32 v[22:23], v[22:23], v[150:151], v[136:137]
	v_pk_fma_f32 v[16:17], v[18:19], v[158:159], v[154:155]
	v_pk_fma_f32 v[18:19], v[130:131], v[152:153], v[138:139]
	v_pk_mul_f32 v[130:131], v[20:21], v[20:21]
	v_pk_mul_f32 v[136:137], v[22:23], v[22:23]
	v_pk_mul_f32 v[138:139], v[16:17], v[16:17]
	v_add_f32_e32 v136, v136, v137
	v_add_f32_e32 v130, v130, v131
	v_pk_mul_f32 v[140:141], v[18:19], v[18:19]
	v_add_f32_e32 v131, v138, v139
	v_add_f32_e32 v130, v130, v136
	v_add_f32_e32 v130, v131, v130
	v_add_f32_e32 v131, v140, v141
	v_add_f32_e32 v130, v131, v130
	v_add_f32_e32 v130, v143, v130
	ds_bpermute_b32 v131, v133, v130
	global_store_dwordx4 v[156:157], v[20:23], off offset:512 nt
	global_store_dwordx4 v[156:157], v[16:19], off offset:528 nt
	s_waitcnt lgkmcnt(0)
	v_add_f32_e32 v130, v130, v131
	ds_bpermute_b32 v131, v135, v130
	s_and_saveexec_b64 s[18:19], vcc
	s_cbranch_execz .LBB0_1055
	s_waitcnt lgkmcnt(0)
	v_add_f32_e32 v130, v130, v131
	ds_write_b32 v134, v130 offset:2560
.LBB0_1055:
	s_or_b64 exec, exec, s[18:19]
	s_mov_b64 s[18:19], 0x2c000
	v_lshl_add_u64 v[140:141], v[128:129], 0, s[18:19]
	v_lshlrev_b64 v[136:137], 1, v[140:141]
	v_lshl_add_u64 v[150:151], s[16:17], 0, v[136:137]
	v_lshl_add_u64 v[152:153], s[12:13], 0, v[136:137]
	s_waitcnt lgkmcnt(0)
	global_load_dwordx4 v[128:131], v[150:151], off
	global_load_dwordx4 v[136:139], v[152:153], off
	global_load_dwordx4 v[168:171], v[150:151], off offset:256
	global_load_dwordx4 v[172:175], v[152:153], off offset:256
	v_mul_f32_e32 v12, 0xbfb8aa3b, v12
	v_mul_f32_e32 v13, 0xbfb8aa3b, v13
	v_mul_f32_e32 v14, 0xbfb8aa3b, v14
	v_mul_f32_e32 v15, 0xbfb8aa3b, v15
	v_mul_f32_e32 v8, 0xbfb8aa3b, v8
	v_mul_f32_e32 v9, 0xbfb8aa3b, v9
	v_mul_f32_e32 v10, 0xbfb8aa3b, v10
	v_mul_f32_e32 v11, 0xbfb8aa3b, v11
	v_exp_f32_e32 v12, v12
	v_exp_f32_e32 v13, v13
	v_exp_f32_e32 v14, v14
	v_exp_f32_e32 v15, v15
	v_exp_f32_e32 v8, v8
	v_exp_f32_e32 v9, v9
	v_exp_f32_e32 v10, v10
	v_exp_f32_e32 v11, v11
	v_add_f32_e32 v12, 1.0, v12
	v_add_f32_e32 v13, 1.0, v13
	v_add_f32_e32 v14, 1.0, v14
	v_add_f32_e32 v15, 1.0, v15
	v_add_f32_e32 v143, 1.0, v8
	v_add_f32_e32 v147, 1.0, v9
	v_add_f32_e32 v149, 1.0, v10
	v_add_f32_e32 v155, 1.0, v11
	v_rcp_f32_e32 v8, v12
	v_rcp_f32_e32 v9, v13
	v_rcp_f32_e32 v14, v14
	v_rcp_f32_e32 v15, v15
	v_rcp_f32_e32 v10, v143
	v_rcp_f32_e32 v11, v147
	v_rcp_f32_e32 v154, v149
	v_rcp_f32_e32 v155, v155
	v_readlane_b32 s16, v254, 0
	v_readlane_b32 s22, v254, 6
	v_readlane_b32 s23, v254, 7
	v_mul_f32_e32 v4, 0xbfb8aa3b, v4
	v_mul_f32_e32 v5, 0xbfb8aa3b, v5
	v_lshl_add_u64 v[140:141], v[140:141], 2, s[22:23]
	v_mul_f32_e32 v0, 0xbfb8aa3b, v0
	v_mul_f32_e32 v1, 0xbfb8aa3b, v1
	v_mul_f32_e32 v6, 0xbfb8aa3b, v6
	v_mul_f32_e32 v7, 0xbfb8aa3b, v7
	v_exp_f32_e32 v4, v4
	v_exp_f32_e32 v5, v5
	v_mul_f32_e32 v2, 0xbfb8aa3b, v2
	v_mul_f32_e32 v3, 0xbfb8aa3b, v3
	v_exp_f32_e32 v0, v0
	v_exp_f32_e32 v1, v1
	v_exp_f32_e32 v6, v6
	v_exp_f32_e32 v7, v7
	v_exp_f32_e32 v2, v2
	v_exp_f32_e32 v3, v3
	v_add_f32_e32 v4, 1.0, v4
	v_add_f32_e32 v5, 1.0, v5
	v_add_f32_e32 v143, 1.0, v0
	v_add_f32_e32 v147, 1.0, v1
	v_add_f32_e32 v6, 1.0, v6
	v_add_f32_e32 v7, 1.0, v7
	v_rcp_f32_e32 v0, v4
	v_rcp_f32_e32 v1, v5
	v_add_f32_e32 v149, 1.0, v2
	v_rcp_f32_e32 v2, v143
	v_rcp_f32_e32 v6, v6
	v_rcp_f32_e32 v7, v7
	v_readlane_b32 s17, v254, 1
	v_readlane_b32 s18, v254, 2
	v_readlane_b32 s19, v254, 3
	v_readlane_b32 s20, v254, 4
	v_readlane_b32 s21, v254, 5
	s_waitcnt vmcnt(3)
	v_lshlrev_b32_e32 v12, 16, v128
	v_and_b32_e32 v13, 0xffff0000, v128
	s_waitcnt vmcnt(2)
	v_lshlrev_b32_e32 v156, 16, v136
	v_and_b32_e32 v157, 0xffff0000, v136
	v_lshlrev_b32_e32 v128, 16, v129
	v_and_b32_e32 v129, 0xffff0000, v129
	v_lshlrev_b32_e32 v136, 16, v137
	v_and_b32_e32 v137, 0xffff0000, v137
	v_lshlrev_b32_e32 v158, 16, v130
	v_and_b32_e32 v159, 0xffff0000, v130
	v_lshlrev_b32_e32 v164, 16, v138
	v_and_b32_e32 v165, 0xffff0000, v138
	v_lshlrev_b32_e32 v130, 16, v131
	v_and_b32_e32 v131, 0xffff0000, v131
	v_lshlrev_b32_e32 v138, 16, v139
	v_and_b32_e32 v139, 0xffff0000, v139
	v_pk_fma_f32 v[12:13], v[8:9], v[156:157], v[12:13]
	v_pk_fma_f32 v[14:15], v[14:15], v[136:137], v[128:129]
	v_pk_fma_f32 v[8:9], v[10:11], v[164:165], v[158:159]
	v_pk_fma_f32 v[10:11], v[154:155], v[138:139], v[130:131]
	global_store_dwordx4 v[140:141], v[12:15], off nt
	global_store_dwordx4 v[140:141], v[8:11], off offset:16 nt
	v_pk_mul_f32 v[4:5], v[12:13], v[12:13]
	v_pk_mul_f32 v[152:153], v[14:15], v[14:15]
	v_add_f32_e32 v151, 1.0, v3
	v_pk_mul_f32 v[154:155], v[8:9], v[8:9]
	v_add_f32_e32 v143, v152, v153
	v_add_f32_e32 v4, v4, v5
	v_rcp_f32_e32 v3, v147
	v_rcp_f32_e32 v150, v149
	v_rcp_f32_e32 v151, v151
	v_pk_mul_f32 v[156:157], v[10:11], v[10:11]
	v_add_f32_e32 v5, v154, v155
	v_add_f32_e32 v4, v4, v143
	v_add_f32_e32 v147, v156, v157
	v_add_f32_e32 v4, v5, v4
	v_add_f32_e32 v143, v147, v4
	s_waitcnt vmcnt(3)
	v_lshlrev_b32_e32 v4, 16, v168
	v_and_b32_e32 v5, 0xffff0000, v168
	s_waitcnt vmcnt(2)
	v_lshlrev_b32_e32 v152, 16, v172
	v_and_b32_e32 v153, 0xffff0000, v172
	v_lshlrev_b32_e32 v128, 16, v169
	v_and_b32_e32 v129, 0xffff0000, v169
	v_lshlrev_b32_e32 v136, 16, v173
	v_and_b32_e32 v137, 0xffff0000, v173
	v_lshlrev_b32_e32 v154, 16, v170
	v_and_b32_e32 v155, 0xffff0000, v170
	v_lshlrev_b32_e32 v156, 16, v174
	v_and_b32_e32 v157, 0xffff0000, v174
	v_lshlrev_b32_e32 v130, 16, v171
	v_and_b32_e32 v131, 0xffff0000, v171
	v_lshlrev_b32_e32 v138, 16, v175
	v_and_b32_e32 v139, 0xffff0000, v175
	v_pk_fma_f32 v[4:5], v[0:1], v[152:153], v[4:5]
	v_pk_fma_f32 v[6:7], v[6:7], v[136:137], v[128:129]
	v_pk_fma_f32 v[0:1], v[2:3], v[156:157], v[154:155]
	v_pk_fma_f32 v[2:3], v[150:151], v[138:139], v[130:131]
	v_pk_mul_f32 v[128:129], v[4:5], v[4:5]
	v_pk_mul_f32 v[130:131], v[6:7], v[6:7]
	v_pk_mul_f32 v[136:137], v[0:1], v[0:1]
	v_add_f32_e32 v130, v130, v131
	v_add_f32_e32 v128, v128, v129
	v_pk_mul_f32 v[138:139], v[2:3], v[2:3]
	v_add_f32_e32 v129, v136, v137
	v_add_f32_e32 v128, v128, v130
	v_add_f32_e32 v128, v129, v128
	v_add_f32_e32 v129, v138, v139
	v_add_f32_e32 v128, v129, v128
	v_add_f32_e32 v128, v143, v128
	ds_bpermute_b32 v129, v133, v128
	global_store_dwordx4 v[140:141], v[4:7], off offset:512 nt
	global_store_dwordx4 v[140:141], v[0:3], off offset:528 nt
	s_waitcnt lgkmcnt(0)
	v_add_f32_e32 v128, v128, v129
	ds_bpermute_b32 v129, v135, v128
	s_and_saveexec_b64 s[12:13], vcc
	s_cbranch_execz .LBB0_1057
	s_waitcnt lgkmcnt(0)
	v_add_f32_e32 v128, v128, v129
	ds_write_b32 v134, v128 offset:2816
